# input-pointer table entries read with scalar loads instead of system-scope flat loads plus readfirstlane
# speedup vs baseline: 1.0487x; 1.0017x over previous
; __device__ __forceinline__ unsigned cvt_pk_bf16(float lo, float hi) { const f32x2_cv v = {lo, hi}; const bf16x2_cv b = __builtin_convertvector(v, bf16x2_cv); return __builtin_bit_cast(unsigned, b); }
; __device__ __forceinline__ int tidx() { int t = threadIdx.x; asm volatile("" : "+v"(t)); return t; }
; __device__ __forceinline__ int bidx() { int b = blockIdx.x; asm volatile("" : "+s"(b)); return b; }
; #define GAS __attribute__((address_space(1)))
; #define INP(p, i) ldp((p).tbl, i)
; __device__ __forceinline__ const float* ldp(const unsigned long long* tbl, int i) {
;     const unsigned long long v = *(const volatile unsigned long long*)(tbl + i);
;     const unsigned lo = __builtin_amdgcn_readfirstlane((unsigned)v), hi = __builtin_amdgcn_readfirstlane((unsigned)(v >> 32));
;     return (const float*)(GAS const float*)(((unsigned long long)hi << 32) | lo); }
; __device__ void phase_x0(const Ctx& p) {
;     const int tid = tidx(); const int wave = __builtin_amdgcn_readfirstlane(tid >> 6), lane = tid & 63;
;     unsigned char* ws = uptr(p.ws);
;     float* rowss = (float*)(ws + OFF_SM + SM_ROWSS); bf16_t* XB = (bf16_t*)(ws + OFF_XB);
;     for (int row = bidx() * 8 + wave; row < T_ALL; row += gridDim.x * 8) {
;         const float* src = row < T_P ? INP(p, 0) + (size_t)row * 1024 : INP(p, 1) + (size_t)(row - T_P) * 1024;
;         float ss = 0.f;
; #pragma unroll
;         for (int i = 0; i < 4; ++i) { const int c = i * 256 + lane * 4; const float4 v = *(const float4*)(src + c);
;             ss += v.x * v.x + v.y * v.y + v.z * v.z + v.w * v.w; u32x2 w; w.x = cvt_pk_bf16(v.x, v.y); w.y = cvt_pk_bf16(v.z, v.w); *(u32x2*)(XB + (size_t)row * 1024 + c) = w; }
;         ss = wsum(ss); if (lane == 0) rowss[row] = ss;
.LBB0_17:
	s_or_b64 exec, exec, s[4:5]
	v_mov_b32_e32 v0, v184
	s_barrier
	s_mov_b32 s10, s86
	v_readfirstlane_b32 s2, v0
	s_ashr_i32 s4, s2, 6
	s_mov_b32 s11, s87
	s_mov_b32 s5, s90
	s_add_u32 s2, s10, 0x2060000
	s_addc_u32 s3, s11, 0
	s_lshl_b32 s5, s5, 3
	s_add_i32 s6, s5, s4
	s_cmpk_gt_i32 s6, 0x43ff
	v_mbcnt_lo_u32_b32 v4, -1, 0
	s_cbranch_scc1 .LBB0_26
	v_mbcnt_hi_u32_b32 v1, -1, v4
	v_and_b32_e32 v2, 64, v1
	v_add_u32_e32 v2, 64, v2
	v_xor_b32_e32 v3, 32, v1
	v_cmp_lt_i32_e32 vcc, v3, v2
	v_and_b32_e32 v0, 63, v0
	v_lshlrev_b32_e32 v12, 2, v0
	v_cndmask_b32_e32 v3, v1, v3, vcc
	v_lshlrev_b32_e32 v5, 2, v3
	v_xor_b32_e32 v3, 16, v1
	v_cmp_lt_i32_e32 vcc, v3, v2
	v_cmp_eq_u32_e64 s[4:5], 0, v0
	v_lshlrev_b32_e32 v0, 3, v0
	v_cndmask_b32_e32 v3, v1, v3, vcc
	v_lshlrev_b32_e32 v6, 2, v3
	v_xor_b32_e32 v3, 8, v1
	v_cmp_lt_i32_e32 vcc, v3, v2
	s_mov_b32 s9, 0
	s_lshl_b32 s15, s50, 3
	v_cndmask_b32_e32 v3, v1, v3, vcc
	v_lshlrev_b32_e32 v7, 2, v3
	v_xor_b32_e32 v3, 4, v1
	v_cmp_lt_i32_e32 vcc, v3, v2
	s_nop 1
	v_cndmask_b32_e32 v3, v1, v3, vcc
	v_lshlrev_b32_e32 v8, 2, v3
	v_xor_b32_e32 v3, 2, v1
	v_cmp_lt_i32_e32 vcc, v3, v2
	s_nop 1
	v_cndmask_b32_e32 v3, v1, v3, vcc
	v_lshlrev_b32_e32 v9, 2, v3
	v_xor_b32_e32 v3, 1, v1
	v_cmp_lt_i32_e32 vcc, v3, v2
	s_nop 1
	v_cndmask_b32_e32 v1, v1, v3, vcc
	v_lshlrev_b32_e32 v10, 2, v1
	v_mov_b32_e32 v1, 0
	v_lshl_add_u64 v[2:3], s[10:11], 0, v[0:1]
	s_mov_b64 s[10:11], 0x2200000
	v_lshl_add_u64 v[2:3], v[2:3], 0, s[10:11]
	v_lshlrev_b32_e32 v0, 2, v12
	v_mov_b64_e32 v[12:13], s[92:93]
	s_waitcnt vmcnt(0) lgkmcnt(0)
	s_load_dword s16, s[92:93], 0x0
	s_load_dword s17, s[92:93], 0x4
	s_waitcnt lgkmcnt(0)
	s_load_dword s18, s[92:93], 0x8
	s_load_dword s19, s[92:93], 0xc
	s_waitcnt lgkmcnt(0)
	s_branch .LBB0_20

; __device__ __forceinline__ int tidx() { int t = threadIdx.x; asm volatile("" : "+v"(t)); return t; }
; #define INP(p, i) ldp((p).tbl, i)
; __device__ void conv_T(const float* __restrict__ src, int ld, int s0, int cnt, int K, const float* __restrict__ scale, bf16_t* __restrict__ dst, int d0, LAS unsigned char* lds, int vb, int nvb) {
;     LAS float* ts = (LAS float*)lds;
;     const int tid = tidx(); const int nkt = K / 256, ntile = (cnt / 32) * nkt;
;     if (vb < 0) return;
;     for (int tile = vb; tile < ntile; tile += nvb) {
;         const int n0 = (tile / nkt) * 32, k0 = (tile % nkt) * 256;
; __device__ void phase_convert_early(const Ctx& p, int l, LAS unsigned char* lds, int vb, int nvb) {
;     unsigned char* ws = uptr(p.ws);
;     const float* win = INP(p, 6) + (size_t)l * 1024 * 5920; const float* nm = INP(p, 5) + l * 1024;
;     conv_T(win, 5920, 0, 1824, 1024, nm, (bf16_t*)(ws + OFF_WRW), 0, lds, vb, nvb);
.LBB0_49:
	v_readlane_b32 s0, v242, 35
	v_readlane_b32 s1, v242, 36
	s_andn2_b64 vcc, exec, s[0:1]
	s_mov_b64 s[36:37], 0
	s_cbranch_vccnz .LBB0_119
	s_mov_b32 s12, s90
	s_mov_b32 s0, s86
	s_mov_b32 s1, s87
	v_mov_b64_e32 v[0:1], s[92:93]
	s_waitcnt vmcnt(0)
	s_max_i32 s10, s12, 63
	s_waitcnt vmcnt(0)
	s_sub_i32 s24, s10, 64
	s_cmpk_gt_u32 s24, 0xe3
	s_waitcnt lgkmcnt(0)
	s_load_dword s5, s[92:93], 0x34
	s_load_dword s4, s[92:93], 0x30
	s_waitcnt lgkmcnt(0)
	s_load_dword s7, s[92:93], 0x2c
	s_load_dword s6, s[92:93], 0x28
	s_waitcnt lgkmcnt(0)
	v_mov_b32_e32 v0, v184
	s_cbranch_scc1 .LBB0_64
	v_and_b32_e32 v1, 7, v0
	s_add_u32 s2, s6, 0x1000
	v_lshlrev_b32_e32 v128, 4, v1
	s_addc_u32 s3, s7, 0
	v_ashrrev_i32_e32 v20, 3, v0
	v_lshl_add_u64 v[2:3], s[4:5], 0, v[128:129]
	s_mov_b64 s[4:5], 0x1720000
	v_ashrrev_i32_e32 v22, 4, v0
	v_lshlrev_b32_e32 v0, 2, v0
	v_lshl_add_u64 v[16:17], v[2:3], 0, s[4:5]
	s_cmp_lg_u64 s[6:7], 0
	v_mul_u32_u24_e32 v1, 0x1010, v1
	v_lshlrev_b32_e32 v2, 2, v20
	s_movk_i32 s6, 0x404
	v_and_b32_e32 v0, 60, v0
	v_add3_u32 v21, 0, v1, v2
	v_mul_lo_u32 v1, v22, s6
	v_lshlrev_b32_e32 v2, 2, v0
	s_cselect_b64 s[4:5], -1, 0
	v_add3_u32 v23, 0, v1, v2
	s_lshl_b32 s13, s24, 8
	s_lshl_b32 s14, s70, 8
	v_lshlrev_b32_e32 v128, 1, v0
	s_mov_b32 s15, s24
	s_branch .LBB0_54

; __device__ __forceinline__ int tidx() { int t = threadIdx.x; asm volatile("" : "+v"(t)); return t; }
; #define INP(p, i) ldp((p).tbl, i)
; __device__ __forceinline__ unsigned short f2bf(float f) { unsigned u = __float_as_uint(f); u += 0x7FFFu + ((u >> 16) & 1u); return (unsigned short)(u >> 16); }
; __device__ void conv_small(const float* __restrict__ src, int ld, int cnt, int K, bf16_t* __restrict__ dst, int vb, int nvb) {
;     if (vb < 0) return;
;     for (int i = vb * 512 + tidx(); i < cnt * K; i += nvb * 512) { const int c = i / K, j = i % K; dst[i] = f2bf(src[(size_t)j * ld + c]); }
; __device__ void phase_convert_early(const Ctx& p, int l, LAS unsigned char* lds, int vb, int nvb) {
;     ...
;     conv_small(INP(p, 9) + (size_t)l * 64 * 512, 512, 512, 64, (bf16_t*)(ws + OFF_SM + SM_W2T), vb, nvb);
.LBB0_69:
	v_mov_b64_e32 v[0:1], s[92:93]
	s_waitcnt vmcnt(0)
	s_cmp_gt_i32 s12, 63
	s_cselect_b64 s[2:3], -1, 0
	s_cmp_lt_i32 s12, 64
	s_waitcnt lgkmcnt(0)
	s_load_dword s7, s[92:93], 0x4c
	s_load_dword s6, s[92:93], 0x48
	s_waitcnt lgkmcnt(0)
	s_cbranch_scc1 .LBB0_79
	v_mov_b32_e32 v1, v184
	s_mov_b32 s4, 0x8000
	v_lshl_add_u32 v0, s24, 9, v1
	v_cmp_gt_i32_e32 vcc, s4, v0
	s_and_saveexec_b64 s[4:5], vcc
	s_cbranch_execz .LBB0_78
	s_add_u32 s6, s6, 0x20000
	s_addc_u32 s7, s7, 0
	s_add_u32 s12, s0, 0x2000000
	s_addc_u32 s13, s1, 0
	s_lshl_b32 s14, s10, 9
	v_readlane_b32 s15, v242, 7
	s_add_i32 s15, s14, s15
	s_add_i32 s14, s14, s74
	v_add_u32_e32 v2, s15, v1
	v_max_i32_e32 v2, 0x8000, v2
	v_add_u32_e32 v2, 0x10000, v2
	v_add_u32_e32 v1, s14, v1
	v_cmp_ne_u32_e32 vcc, v2, v1
	s_mov_b64 s[22:23], -1
	s_nop 0
	v_cndmask_b32_e64 v3, 1, 2, vcc
	v_subb_co_u32_e32 v1, vcc, v2, v1, vcc
	v_mul_hi_u32 v2, v1, v185
	v_mul_lo_u32 v4, v2, s78
	v_sub_u32_e32 v1, v1, v4
	v_add_u32_e32 v4, 1, v2
	v_cmp_le_u32_e32 vcc, s78, v1
	s_nop 1
	v_cndmask_b32_e32 v2, v2, v4, vcc
	v_subrev_u32_e32 v4, s78, v1
	v_cndmask_b32_e32 v1, v1, v4, vcc
	v_add_u32_e32 v4, 1, v2
	v_cmp_le_u32_e32 vcc, s78, v1
	s_nop 1
	v_cndmask_b32_e32 v1, v2, v4, vcc
	v_add_u32_e32 v3, v3, v1
	v_cmp_lt_u32_e32 vcc, 1, v3
	s_and_saveexec_b64 s[20:21], vcc
	s_cbranch_execz .LBB0_75
	v_readlane_b32 s14, v242, 3
	v_and_b32_e32 v4, -2, v3
	v_readlane_b32 s15, v242, 4
	v_add_u32_e32 v2, s14, v0
	s_mov_b64 s[22:23], 0
	v_add_u32_e32 v1, s15, v0
	v_mov_b32_e32 v5, v4
	v_readlane_b32 s14, v242, 8

; __device__ __forceinline__ int tidx() { int t = threadIdx.x; asm volatile("" : "+v"(t)); return t; }
; #define INP(p, i) ldp((p).tbl, i)
; __device__ __forceinline__ unsigned short f2bf(float f) { unsigned u = __float_as_uint(f); u += 0x7FFFu + ((u >> 16) & 1u); return (unsigned short)(u >> 16); }
; __device__ void conv_small(const float* __restrict__ src, int ld, int cnt, int K, bf16_t* __restrict__ dst, int vb, int nvb) {
;     if (vb < 0) return;
;     for (int i = vb * 512 + tidx(); i < cnt * K; i += nvb * 512) { const int c = i / K, j = i % K; dst[i] = f2bf(src[(size_t)j * ld + c]); }
; __device__ void phase_convert_early(const Ctx& p, int l, LAS unsigned char* lds, int vb, int nvb) {
;     ...
;     conv_small(INP(p, 11) + (size_t)l * 64 * 512, 512, 512, 64, (bf16_t*)(ws + OFF_SM + SM_A2T), vb, nvb);
.LBB0_79:
	v_mov_b64_e32 v[0:1], s[92:93]
	s_waitcnt vmcnt(0)
	v_cndmask_b32_e64 v2, 0, 1, s[2:3]
	v_cmp_ne_u32_e64 s[38:39], 1, v2
	s_andn2_b64 vcc, exec, s[2:3]
	s_waitcnt lgkmcnt(0)
	s_load_dword s5, s[92:93], 0x5c
	s_load_dword s4, s[92:93], 0x58
	s_waitcnt lgkmcnt(0)
	s_cbranch_vccnz .LBB0_89
	v_mov_b32_e32 v1, v184
	s_mov_b32 s2, 0x8000
	v_lshl_add_u32 v0, s24, 9, v1
	v_cmp_gt_i32_e32 vcc, s2, v0
	s_and_saveexec_b64 s[2:3], vcc
	s_cbranch_execz .LBB0_88
	s_add_u32 s4, s4, 0x20000
	s_addc_u32 s5, s5, 0
	s_add_u32 s6, s0, 0x2010000
	s_addc_u32 s7, s1, 0
	s_lshl_b32 s12, s10, 9
	v_readlane_b32 s13, v242, 7
	s_add_i32 s13, s12, s13
	s_add_i32 s12, s12, s74
	v_add_u32_e32 v2, s13, v1
	v_max_i32_e32 v2, 0x8000, v2
	v_add_u32_e32 v2, 0x10000, v2
	v_add_u32_e32 v1, s12, v1
	v_cmp_ne_u32_e32 vcc, v2, v1
	s_mov_b64 s[20:21], -1
	s_nop 0
	v_cndmask_b32_e64 v3, 1, 2, vcc
	v_subb_co_u32_e32 v1, vcc, v2, v1, vcc
	v_mul_hi_u32 v2, v1, v185
	v_mul_lo_u32 v4, v2, s78
	v_sub_u32_e32 v1, v1, v4
	v_add_u32_e32 v4, 1, v2
	v_cmp_le_u32_e32 vcc, s78, v1
	s_nop 1
	v_cndmask_b32_e32 v2, v2, v4, vcc
	v_subrev_u32_e32 v4, s78, v1
	v_cndmask_b32_e32 v1, v1, v4, vcc
	v_add_u32_e32 v4, 1, v2
	v_cmp_le_u32_e32 vcc, s78, v1
	s_nop 1
	v_cndmask_b32_e32 v1, v2, v4, vcc
	v_add_u32_e32 v3, v3, v1
	v_cmp_lt_u32_e32 vcc, 1, v3
	s_and_saveexec_b64 s[12:13], vcc
	s_cbranch_execz .LBB0_85
	v_readlane_b32 s14, v242, 3
	v_and_b32_e32 v4, -2, v3
	v_readlane_b32 s15, v242, 4
	v_add_u32_e32 v2, s14, v0
	s_mov_b64 s[20:21], 0
	v_add_u32_e32 v1, s15, v0
	v_mov_b32_e32 v5, v4
	v_readlane_b32 s14, v242, 8

; __device__ __forceinline__ int tidx() { int t = threadIdx.x; asm volatile("" : "+v"(t)); return t; }
; #define INP(p, i) ldp((p).tbl, i)
; __device__ __forceinline__ unsigned short f2bf(float f) { unsigned u = __float_as_uint(f); u += 0x7FFFu + ((u >> 16) & 1u); return (unsigned short)(u >> 16); }
; __device__ void conv_small(const float* __restrict__ src, int ld, int cnt, int K, bf16_t* __restrict__ dst, int vb, int nvb) {
;     if (vb < 0) return;
;     for (int i = vb * 512 + tidx(); i < cnt * K; i += nvb * 512) { const int c = i / K, j = i % K; dst[i] = f2bf(src[(size_t)j * ld + c]); }
; __device__ void phase_convert_early(const Ctx& p, int l, LAS unsigned char* lds, int vb, int nvb) {
;     ...
;     conv_small(INP(p, 12) + (size_t)l * 160 * 512, 512, 512, 160, (bf16_t*)(ws + OFF_SM + SM_G2T), vb, nvb);
.LBB0_89:
	v_mov_b64_e32 v[0:1], s[92:93]
	s_waitcnt vmcnt(0)
	s_and_b64 vcc, exec, s[38:39]
	s_waitcnt lgkmcnt(0)
	s_load_dword s5, s[92:93], 0x64
	s_load_dword s4, s[92:93], 0x60
	s_waitcnt lgkmcnt(0)
	s_cbranch_vccnz .LBB0_99
	v_mov_b32_e32 v1, v184
	s_mov_b32 s2, 0x14000
	v_lshl_add_u32 v0, s24, 9, v1
	v_cmp_gt_i32_e32 vcc, s2, v0
	s_and_saveexec_b64 s[2:3], vcc
	s_cbranch_execz .LBB0_98
	s_add_u32 s4, s4, 0x50000
	s_addc_u32 s5, s5, 0
	s_add_u32 s6, s0, 0x2020000
	s_addc_u32 s7, s1, 0
	s_lshl_b32 s12, s10, 9
	v_readlane_b32 s13, v242, 7
	s_add_i32 s13, s12, s13
	s_add_i32 s12, s12, s74
	v_add_u32_e32 v2, s13, v1
	v_max_i32_e32 v2, 0x14000, v2
	v_add_u32_e32 v2, 0x10000, v2
	v_add_u32_e32 v1, s12, v1
	v_cmp_ne_u32_e32 vcc, v2, v1
	s_mov_b64 s[20:21], -1
	s_nop 0
	v_cndmask_b32_e64 v3, 1, 2, vcc
	v_subb_co_u32_e32 v1, vcc, v2, v1, vcc
	v_mul_hi_u32 v2, v1, v185
	v_mul_lo_u32 v4, v2, s78
	v_sub_u32_e32 v1, v1, v4
	v_add_u32_e32 v4, 1, v2
	v_cmp_le_u32_e32 vcc, s78, v1
	s_nop 1
	v_cndmask_b32_e32 v2, v2, v4, vcc
	v_subrev_u32_e32 v4, s78, v1
	v_cndmask_b32_e32 v1, v1, v4, vcc
	v_add_u32_e32 v4, 1, v2
	v_cmp_le_u32_e32 vcc, s78, v1
	s_nop 1
	v_cndmask_b32_e32 v1, v2, v4, vcc
	v_add_u32_e32 v3, v3, v1
	v_cmp_lt_u32_e32 vcc, 1, v3
	s_and_saveexec_b64 s[12:13], vcc
	s_cbranch_execz .LBB0_95
	v_readlane_b32 s14, v242, 3
	v_and_b32_e32 v4, -2, v3
	v_readlane_b32 s15, v242, 4
	v_add_u32_e32 v2, s14, v0
	s_mov_b64 s[20:21], 0
	v_add_u32_e32 v1, s15, v0
	v_mov_b32_e32 v5, v4
	v_readlane_b32 s14, v242, 8
	s_mov_b32 s15, 0x66666667

; __device__ __forceinline__ int tidx() { int t = threadIdx.x; asm volatile("" : "+v"(t)); return t; }
; #define INP(p, i) ldp((p).tbl, i)
; __device__ __forceinline__ unsigned short f2bf(float f) { unsigned u = __float_as_uint(f); u += 0x7FFFu + ((u >> 16) & 1u); return (unsigned short)(u >> 16); }
; __device__ void conv_small(const float* __restrict__ src, int ld, int cnt, int K, bf16_t* __restrict__ dst, int vb, int nvb) {
;     if (vb < 0) return;
;     for (int i = vb * 512 + tidx(); i < cnt * K; i += nvb * 512) { const int c = i / K, j = i % K; dst[i] = f2bf(src[(size_t)j * ld + c]); }
; __device__ void phase_convert_early(const Ctx& p, int l, LAS unsigned char* lds, int vb, int nvb) {
;     ...
;         conv_small(INP(p, 14), 32, 32, 512, (bf16_t*)(ws + OFF_SM + SM_V1T), vb, nvb);
.LBB0_99:
	v_mov_b64_e32 v[0:1], s[92:93]
	s_waitcnt vmcnt(0)
	s_and_b64 vcc, exec, s[38:39]
	s_waitcnt lgkmcnt(0)
	s_load_dword s3, s[92:93], 0x74
	s_load_dword s2, s[92:93], 0x70
	s_waitcnt lgkmcnt(0)
	s_cbranch_vccnz .LBB0_109
	v_mov_b32_e32 v1, v184
	s_movk_i32 s4, 0x4000
	v_lshl_add_u32 v0, s24, 9, v1
	v_cmp_gt_i32_e32 vcc, s4, v0
	s_and_saveexec_b64 s[4:5], vcc
	s_cbranch_execz .LBB0_108
	s_add_u32 s6, s0, 0x2048000
	s_addc_u32 s7, s1, 0
	s_lshl_b32 s12, s10, 9
	v_readlane_b32 s13, v242, 7
	s_add_i32 s13, s12, s13
	s_add_i32 s12, s12, s74
	v_add_u32_e32 v2, s13, v1
	v_max_i32_e32 v2, 0x4000, v2
	v_add_u32_e32 v2, 0x10000, v2
	v_add_u32_e32 v1, s12, v1
	v_cmp_ne_u32_e32 vcc, v2, v1
	s_mov_b64 s[20:21], -1
	s_nop 0
	v_cndmask_b32_e64 v3, 1, 2, vcc
	v_subb_co_u32_e32 v1, vcc, v2, v1, vcc
	v_mul_hi_u32 v2, v1, v185
	v_mul_lo_u32 v4, v2, s78
	v_sub_u32_e32 v1, v1, v4
	v_add_u32_e32 v4, 1, v2
	v_cmp_le_u32_e32 vcc, s78, v1
	s_nop 1
	v_cndmask_b32_e32 v2, v2, v4, vcc
	v_subrev_u32_e32 v4, s78, v1
	v_cndmask_b32_e32 v1, v1, v4, vcc
	v_add_u32_e32 v4, 1, v2
	v_cmp_le_u32_e32 vcc, s78, v1
	s_nop 1
	v_cndmask_b32_e32 v1, v2, v4, vcc
	v_add_u32_e32 v3, v3, v1
	v_cmp_lt_u32_e32 vcc, 1, v3
	s_and_saveexec_b64 s[12:13], vcc
	s_cbranch_execz .LBB0_105
	v_readlane_b32 s14, v242, 3
	v_and_b32_e32 v4, -2, v3
	v_readlane_b32 s15, v242, 4
	v_add_u32_e32 v2, s14, v0
	s_mov_b64 s[20:21], 0
	v_add_u32_e32 v1, s15, v0
	v_mov_b32_e32 v5, v4
	v_readlane_b32 s14, v242, 8

; __device__ __forceinline__ int tidx() { int t = threadIdx.x; asm volatile("" : "+v"(t)); return t; }
; #define INP(p, i) ldp((p).tbl, i)
; __device__ __forceinline__ unsigned short f2bf(float f) { unsigned u = __float_as_uint(f); u += 0x7FFFu + ((u >> 16) & 1u); return (unsigned short)(u >> 16); }
; __device__ void conv_small(const float* __restrict__ src, int ld, int cnt, int K, bf16_t* __restrict__ dst, int vb, int nvb) {
;     if (vb < 0) return;
;     for (int i = vb * 512 + tidx(); i < cnt * K; i += nvb * 512) { const int c = i / K, j = i % K; dst[i] = f2bf(src[(size_t)j * ld + c]); }
; __device__ void phase_convert_early(const Ctx& p, int l, LAS unsigned char* lds, int vb, int nvb) {
;     ...
;         conv_small(INP(p, 15), 512, 512, 32, (bf16_t*)(ws + OFF_SM + SM_V2T), vb, nvb);
.LBB0_109:
	v_mov_b64_e32 v[0:1], s[92:93]
	s_waitcnt vmcnt(0)
	s_and_b64 vcc, exec, s[38:39]
	v_readlane_b32 s39, v242, 28
	s_movk_i32 s16, 0x3fff
	s_mov_b32 s38, 0x1ffff
	s_waitcnt lgkmcnt(0)
	s_load_dword s3, s[92:93], 0x7c
	s_load_dword s2, s[92:93], 0x78
	s_waitcnt lgkmcnt(0)
	s_cbranch_vccnz .LBB0_119
	v_mov_b32_e32 v1, v184
	s_movk_i32 s4, 0x4000
	v_lshl_add_u32 v0, s24, 9, v1
	v_cmp_gt_i32_e32 vcc, s4, v0
	s_and_saveexec_b64 s[4:5], vcc
	s_cbranch_execz .LBB0_118
	s_add_u32 s0, s0, 0x2050000
	s_addc_u32 s1, s1, 0
	s_lshl_b32 s6, s10, 9
	v_readlane_b32 s7, v242, 7
	s_add_i32 s7, s6, s7
	s_add_i32 s6, s6, s74
	v_add_u32_e32 v2, s7, v1
	v_max_i32_e32 v2, 0x4000, v2
	v_add_u32_e32 v2, 0x10000, v2
	v_add_u32_e32 v1, s6, v1
	v_cmp_ne_u32_e32 vcc, v2, v1
	s_mov_b64 s[12:13], -1
	s_nop 0
	v_cndmask_b32_e64 v3, 1, 2, vcc
	v_subb_co_u32_e32 v1, vcc, v2, v1, vcc
	v_mul_hi_u32 v2, v1, v185
	v_mul_lo_u32 v4, v2, s78
	v_sub_u32_e32 v1, v1, v4
	v_add_u32_e32 v4, 1, v2
	v_cmp_le_u32_e32 vcc, s78, v1
	s_nop 1
	v_cndmask_b32_e32 v2, v2, v4, vcc
	v_subrev_u32_e32 v4, s78, v1
	v_cndmask_b32_e32 v1, v1, v4, vcc
	v_add_u32_e32 v4, 1, v2
	v_cmp_le_u32_e32 vcc, s78, v1
	s_nop 1
	v_cndmask_b32_e32 v1, v2, v4, vcc
	v_add_u32_e32 v3, v3, v1
	v_cmp_lt_u32_e32 vcc, 1, v3
	s_and_saveexec_b64 s[6:7], vcc
	s_cbranch_execz .LBB0_115
	v_readlane_b32 s12, v242, 3
	v_and_b32_e32 v4, -2, v3
	v_readlane_b32 s13, v242, 4
	v_add_u32_e32 v2, s12, v0
	v_mov_b32_e32 v5, v4
	v_add_u32_e32 v1, s13, v0
	s_mov_b64 s[12:13], 0
	v_readlane_b32 s10, v242, 8

; #define INP(p, i) ldp((p).tbl, i)
; __global__ void __launch_bounds__(512, 2) mega_fwd(Params prm) {
;     ...
;         case 11: { GEMM_PRO; EpiResid E; E.X = p.out; E.XB = XB; E.rowss_out = rs_ffn; E.Xp0 = l == 0 ? INP(p, 0) : nullptr; E.Xs0 = l == 0 ? INP(p, 1) : nullptr;
.LBB0_121:
	v_readlane_b32 s2, v242, 35
	v_readlane_b32 s3, v242, 36
	s_mov_b32 s10, s86
	s_mov_b32 s46, s87
	v_cndmask_b32_e64 v0, 0, 1, s[2:3]
	s_mov_b64 s[0:1], 0
	v_cmp_ne_u32_e64 s[78:79], 1, v0
	s_andn2_b64 vcc, exec, s[2:3]
	s_mov_b64 s[4:5], 0
	s_cbranch_vccnz .LBB0_123
	v_mov_b64_e32 v[0:1], s[92:93]
	s_waitcnt vmcnt(0) lgkmcnt(0)
	s_load_dword s1, s[92:93], 0x4
	s_waitcnt vmcnt(0)
	s_load_dword s0, s[92:93], 0x0
	s_waitcnt lgkmcnt(0)
	s_waitcnt lgkmcnt(0)
	s_load_dword s5, s[92:93], 0xc
	s_load_dword s4, s[92:93], 0x8
	s_waitcnt lgkmcnt(0)

; #define INP(p, i) ldp((p).tbl, i)
; __global__ void __launch_bounds__(512, 2) mega_fwd(Params prm) {
;     ...
;                    xcd_barrier(xb);
;                    finalize_sample(p, rs_ffn, OFF_GPART, 4, l == 0 ? INP(p, 1) : nullptr); } break;
.LBB0_269:
	s_or_b64 exec, exec, s[0:1]
	s_and_b64 vcc, exec, s[78:79]
	s_mov_b64 s[4:5], 0
	s_waitcnt lgkmcnt(0)
	s_barrier
	s_cbranch_vccnz .LBB0_271
	v_mov_b64_e32 v[0:1], s[92:93]
	s_waitcnt vmcnt(0) lgkmcnt(0)
	s_load_dword s5, s[92:93], 0xc
	s_load_dword s4, s[92:93], 0x8
	s_waitcnt lgkmcnt(0)

; __device__ __forceinline__ int tidx() { int t = threadIdx.x; asm volatile("" : "+v"(t)); return t; }
; __device__ __forceinline__ int bidx() { int b = blockIdx.x; asm volatile("" : "+s"(b)); return b; }
; #define INP(p, i) ldp((p).tbl, i)
; __device__ __forceinline__ float lb_of(const Ctx& p, int l, int c) { if (l == 0) return 0.f; const float* z = INP(p, 21); const float z0 = z[c], z1 = z[512 + c]; return __builtin_amdgcn_rcpf(1.0f + __expf(z0 - z1)); }
; __device__ void phase_hgrn_fix(const Ctx& p, int l, LAS unsigned char* lds) {
;     unsigned char* ws = uptr(p.ws);
;     const bf16_t* PH = (const bf16_t*)(ws + OFF_A); const bf16_t* OH = (const bf16_t*)(ws + OFF_B + 2 * SLOT); const float* UCH = (const float*)(ws + OFF_B + 3 * SLOT);
;     const float* PGC = (const float*)(ws + OFF_PGC); const bf16_t* OH1 = (const bf16_t*)(ws + OFF_B + 5 * SLOT);
;     bf16_t* YB = (bf16_t*)(ws + OFF_B + SLOT);
;     const int tid = tidx(); const int wave = __builtin_amdgcn_readfirstlane(tid >> 6), lane = tid & 63, fr = lane & 15, fq = lane >> 4;
;     const float* nw = INP(p, 22) + l * 512;
;     constexpr int QS = 136;
;     LAS bf16_t* QT = (LAS bf16_t*)(lds + wave * 16384);
;     for (int item = bidx() * 8 + wave; item < 2048; item += gridDim.x * 8) {
;         const int tq = item & 3, idx = item >> 2, h = idx & 3, c = (idx >> 2) & 63, b = idx >> 8;
;         const float lbl = lb_of(p, l, h * 128 + lane), lbh = lb_of(p, l, h * 128 + 64 + lane);
;         const int tbase = b * 8192 + c * 128 + tq * 32;
;         float rl = 1.f, rh = 1.f;
;         if (tq) { rl = PGC[(size_t)idx * 384 + (tq - 1) * 128 + lane]; rh = PGC[(size_t)idx * 384 + (tq - 1) * 128 + 64 + lane]; }
.LBB0_434:
	s_and_b64 vcc, exec, s[0:1]
	s_cbranch_vccz .LBB0_453
	s_mov_b32 s21, s87
	s_mov_b32 s20, s86
	v_mov_b32_e32 v0, v184
	v_mov_b64_e32 v[2:3], s[92:93]
	s_waitcnt vmcnt(0)
	v_readfirstlane_b32 s4, v0
	s_ashr_i32 s1, s4, 6
	s_and_b64 s[2:3], s[34:35], exec
	s_cselect_b32 s2, 0x800, 0
	s_mov_b32 s0, s90
	v_and_b32_e32 v116, 63, v0
	s_waitcnt lgkmcnt(0)
	s_load_dword s5, s[92:93], 0xb0
	s_load_dword s3, s[92:93], 0xb4
	s_waitcnt lgkmcnt(0)
	s_add_u32 s22, s5, s2
	s_addc_u32 s23, s3, 0
	s_lshl_b32 s2, s0, 3
	s_add_i32 s5, s2, s1
	s_cmpk_gt_i32 s5, 0x7ff
	s_cbranch_scc1 .LBB0_447
	s_add_u32 s38, s20, 0x5500000
	v_and_b32_e32 v117, 15, v0
	s_addc_u32 s39, s21, 0
	s_lshl_b32 s2, s1, 14
	v_lshlrev_b32_e32 v128, 2, v117
	s_add_i32 s10, s2, 0
	v_lshrrev_b32_e32 v3, 4, v116
	v_lshl_add_u64 v[0:1], s[20:21], 0, v[128:129]
	s_mov_b64 s[2:3], 0xcc00000
	v_lshl_add_u64 v[118:119], v[0:1], 0, s[2:3]
	v_lshlrev_b32_e32 v128, 3, v3
	v_mul_u32_u24_e32 v1, 0x110, v117
	v_and_b32_e32 v0, 48, v116
	v_and_b32_e32 v6, 64, v189
	v_add3_u32 v192, s10, v1, v0
	v_lshl_add_u64 v[4:5], s[20:21], 0, v[128:129]
	s_mov_b64 s[2:3], 0xbb00000
	v_xor_b32_e32 v1, 16, v189
	v_add_u32_e32 v6, 64, v6
	v_lshl_add_u64 v[120:121], v[4:5], 0, s[2:3]
	s_mov_b64 s[2:3], 0xee00000
	v_cmp_lt_i32_e32 vcc, v1, v6
	v_lshl_add_u64 v[122:123], v[4:5], 0, s[2:3]
	s_mov_b64 s[2:3], 0xaa00000
	v_cndmask_b32_e32 v1, v189, v1, vcc
	v_lshlrev_b32_e32 v193, 2, v1
	v_xor_b32_e32 v1, 32, v189
	v_lshl_add_u64 v[126:127], v[4:5], 0, s[2:3]
	s_bfe_u32 s2, s4, 0x20006
	v_cmp_lt_i32_e32 vcc, v1, v6
	s_lshl_b32 s12, s2, 5
	s_cmp_lg_u32 s2, 0
	v_cndmask_b32_e32 v1, v189, v1, vcc
	v_lshlrev_b32_e32 v194, 2, v1
	v_mov_b32_e32 v1, v129
	s_cselect_b64 s[6:7], -1, 0
	s_lshl_b32 s2, s2, 9
	v_lshl_add_u64 v[124:125], s[22:23], 0, v[0:1]
	s_add_u32 s13, s20, s2
	v_lshlrev_b32_e32 v0, 10, v3
	v_lshlrev_b32_e32 v128, 1, v116
	v_lshlrev_b32_e32 v2, 2, v3
	s_addc_u32 s24, s21, 0
	v_or_b32_e32 v4, 0x1000, v0
	v_or_b32_e32 v6, 0x2000, v0
	v_or_b32_e32 v8, 0x3000, v0
	v_lshl_add_u64 v[10:11], s[20:21], 0, v[128:129]
	s_mov_b64 s[2:3], 0x5507480
	s_lshl_b32 s0, s0, 6
	s_lshl_b32 s1, s1, 3
	v_add_u32_e32 v195, s10, v128
	v_lshl_add_u64 v[148:149], v[10:11], 0, s[2:3]
	s_add_i32 s25, s0, s1
	v_lshlrev_b32_e32 v150, 2, v116
	v_lshlrev_b32_e32 v128, 2, v0
	v_lshlrev_b32_e32 v152, 2, v4
	v_lshlrev_b32_e32 v154, 2, v6
	v_lshlrev_b32_e32 v156, 2, v8
	v_lshlrev_b32_e32 v158, 1, v2
.LBB0_437:
	s_ashr_i32 s2, s5, 2
	s_lshl_b32 s0, s2, 7
	s_and_b32 s26, s0, 0x180
	v_or_b32_e32 v0, s26, v116
	v_cndmask_b32_e64 v2, 0, 1, s[34:35]
	v_mov_b32_e32 v1, 0
	v_cmp_ne_u32_e64 s[0:1], 1, v2
	s_andn2_b64 vcc, exec, s[34:35]
	v_lshlrev_b32_e32 v2, 2, v0
	v_mov_b32_e32 v0, 0
	s_cbranch_vccnz .LBB0_441
	v_mov_b64_e32 v[4:5], s[92:93]
	s_waitcnt vmcnt(0) lgkmcnt(0)
	s_load_dword s15, s[92:93], 0xac
	s_load_dword s14, s[92:93], 0xa8
	s_waitcnt lgkmcnt(0)
	s_nop 4
	global_load_dword v0, v2, s[14:15]
	global_load_dword v3, v2, s[14:15] offset:2048
	s_waitcnt vmcnt(0)
	v_sub_f32_e32 v0, v0, v3
	v_mul_f32_e32 v0, 0x3fb8aa3b, v0
	v_exp_f32_e32 v0, v0
	s_nop 0
	v_add_f32_e32 v0, 1.0, v0
	v_rcp_f32_e32 v0, v0
	s_and_b64 vcc, exec, s[0:1]
	s_cbranch_vccz .LBB0_442

; __device__ __forceinline__ float lb_of(const Ctx& p, int l, int c) { if (l == 0) return 0.f; const float* z = INP(p, 21); const float z0 = z[c], z1 = z[512 + c]; return __builtin_amdgcn_rcpf(1.0f + __expf(z0 - z1)); }
; __device__ void phase_hgrn_fix(const Ctx& p, int l, LAS unsigned char* lds) {
;     ...
;         const float lbl = lb_of(p, l, h * 128 + lane), lbh = lb_of(p, l, h * 128 + 64 + lane);
.LBB0_442:
	v_mov_b64_e32 v[4:5], s[92:93]
	s_waitcnt vmcnt(0) lgkmcnt(0)
	s_load_dword s1, s[92:93], 0xac
	s_load_dword s0, s[92:93], 0xa8
	s_waitcnt lgkmcnt(0)
	s_nop 4
	global_load_dword v1, v2, s[0:1] offset:256
	s_nop 0
	global_load_dword v2, v2, s[0:1] offset:2304
	s_waitcnt vmcnt(0)
	v_sub_f32_e32 v1, v1, v2
	v_mul_f32_e32 v1, 0x3fb8aa3b, v1
	v_exp_f32_e32 v1, v1
	s_nop 0
	v_add_f32_e32 v1, 1.0, v1
	v_rcp_f32_e32 v1, v1
	s_andn2_b64 vcc, exec, s[6:7]
	s_cbranch_vccz .LBB0_440

; __device__ __forceinline__ int bidx() { int b = blockIdx.x; asm volatile("" : "+s"(b)); return b; }
; #define INP(p, i) ldp((p).tbl, i)
; __device__ __forceinline__ float lb_of(const Ctx& p, int l, int c) { if (l == 0) return 0.f; const float* z = INP(p, 21); const float z0 = z[c], z1 = z[512 + c]; return __builtin_amdgcn_rcpf(1.0f + __expf(z0 - z1)); }
; __device__ __forceinline__ void hgrn_scan(const bf16_t* __restrict__ PH, int t0, int nsteps, int h, int half, int kh, int lane, float lb, f2 (&S)[32], float& cp, bf16_t* __restrict__ OHp, float* __restrict__ ckp, LAS float* L) {
;     const bf16_t* row = PH + (size_t)t0 * 2048 + h * 128 + kh * 64 + lane; const int voff = 1024 + (half - kh) * 64;
; __device__ void phase_hgrn_scan(const Ctx& p, int l, LAS unsigned char* lds) {
;     ...
;         for (int item = bidx() * 2 + wave; item < 512; item += gridDim.x * 2) {
;             const int kh = item & 1, half = (item >> 1) & 1, h = (item >> 2) & 3, s = item >> 4;
;             const size_t so = (((size_t)l * 32 + s) * 4 + h) * 16384 + (size_t)(kh * 64) * 128 + half * 64 + lane;
;             f2 S[32];
;             const float* stp = INP(p, 4) + so;
; #pragma unroll
;             for (int k = 0; k < 32; ++k) S[k] = (f2){stp[(2 * k) * 128], stp[(2 * k + 1) * 128]};
;             float cp = 1.f;
;             hgrn_scan(PH, T_P + s * 32, 32, h, half, kh, lane, lb_of(p, l, h * 128 + kh * 64 + lane), S, cp, kh ? OH1 : OH0, nullptr, L);
.Lhs_role_s:
	s_mov_b32 s0, s90
	s_cmpk_gt_u32 s0, 0xff
	s_cbranch_scc1 .LBB0_486
	s_and_b32 s1, s0, 1
	s_bfe_u32 s2, s0, 0x20001
	s_lshr_b32 s3, s0, 3
	s_lshl_b32 s4, s3, 5
	s_add_i32 s4, s4, 0x4000
	s_mov_b32 s36, 8
	s_and_b64 s[6:7], s[34:35], exec
	s_cselect_b32 s5, 32, 0
	s_add_i32 s5, s5, s3
	s_lshl_b32 s5, s5, 2
	s_add_i32 s5, s5, s2
	s_lshr_b32 s7, s5, 16
	s_lshl_b32 s6, s5, 16
	s_lshl_b32 s5, s1, 15
	s_add_u32 s6, s6, s5
	s_addc_u32 s7, s7, 0
	s_add_u32 s40, s84, 0x4df9200
	s_addc_u32 s41, s85, 0
	s_add_u32 s40, s40, s6
	s_addc_u32 s41, s41, s7
	v_mov_b64_e32 v[0:1], s[92:93]
	s_waitcnt vmcnt(0) lgkmcnt(0)
	s_load_dword s30, s[92:93], 0x20
	s_load_dword s31, s[92:93], 0x24
	s_waitcnt lgkmcnt(0)
	s_add_u32 s30, s30, s6
	s_addc_u32 s31, s31, s7
.Lhs_common:
	v_and_b32_e32 v146, 63, v184
	s_mov_b32 s5, 0xee00000
	s_cmp_eq_u32 s1, 0
	s_cselect_b32 s5, 0xbb00000, s5
	s_add_u32 s26, s86, s5
	s_addc_u32 s27, s87, 0
	s_lshl_b32 s5, s2, 7
	s_lshl_b32 s6, s1, 6
	s_add_i32 s6, s6, s5
	v_add_u32_e32 v140, s6, v146
	s_lshl_b32 s7, s4, 12
	v_lshl_add_u32 v136, v140, 1, s7
	v_add_u32_e32 v141, s5, v146
	v_lshlrev_b32_e32 v141, 1, v141
	s_add_i32 s12, s7, 0x800
	v_add_u32_e32 v137, s12, v141
	s_lshl_b32 s12, s4, 10
	v_add_u32_e32 v138, s12, v141
	s_lshl_b32 s12, s38, 10
	v_lshl_add_u32 v134, v146, 2, s12
	v_mov_b32_e32 v135, s12
	v_lshlrev_b32_e32 v147, 2, v146
	v_mov_b32_e32 v130, 0
	s_andn2_b64 vcc, exec, s[34:35]
	s_cbranch_vccnz .Lhs_lb0
	v_mov_b64_e32 v[0:1], s[92:93]
	s_waitcnt vmcnt(0) lgkmcnt(0)
	s_load_dword s12, s[92:93], 0xa8
	s_load_dword s13, s[92:93], 0xac
	s_waitcnt lgkmcnt(0)
	v_lshlrev_b32_e32 v140, 2, v140
	s_nop 3
	global_load_dword v141, v140, s[12:13]
	global_load_dword v142, v140, s[12:13] offset:2048
	s_waitcnt vmcnt(0)
	v_sub_f32_e32 v141, v141, v142
	v_mul_f32_e32 v141, 0x3fb8aa3b, v141
	v_exp_f32_e32 v141, v141
	s_nop 0
	v_add_f32_e32 v141, 1.0, v141
	v_rcp_f32_e32 v130, v141
	s_nop 0

; __device__ __forceinline__ int tidx() { int t = threadIdx.x; asm volatile("" : "+v"(t)); return t; }
; #define INP(p, i) ldp((p).tbl, i)
; __device__ void conv_T(const float* __restrict__ src, int ld, int s0, int cnt, int K, const float* __restrict__ scale, bf16_t* __restrict__ dst, int d0, LAS unsigned char* lds, int vb, int nvb) {
;     LAS float* ts = (LAS float*)lds;
;     const int tid = tidx(); const int nkt = K / 256, ntile = (cnt / 32) * nkt;
;     if (vb < 0) return;
;     for (int tile = vb; tile < ntile; tile += nvb) {
;         const int n0 = (tile / nkt) * 32, k0 = (tile % nkt) * 256;
; __device__ void phase_convert_late(const Ctx& p, int l, LAS unsigned char* lds, int vb, int nvb) {
;     unsigned char* ws = uptr(p.ws);
;     const float* win = INP(p, 6) + (size_t)l * 1024 * 5920; const float* nm = INP(p, 5) + l * 1024;
;     conv_T(win, 5920, 3872, 1024, 1024, nm, (bf16_t*)(ws + OFF_WGA), 0, lds, vb, nvb);
.LBB0_500:
	s_mov_b32 s0, s90
	s_mov_b32 s24, s86
	s_mov_b32 s25, s87
	v_mov_b64_e32 v[0:1], s[92:93]
	s_waitcnt vmcnt(0)
	s_max_i32 s0, s0, 31
	s_waitcnt vmcnt(0)
	s_sub_i32 s10, s0, 32
	s_and_b64 s[0:1], s[34:35], exec
	s_cselect_b32 s0, 0x1720000, 0
	s_mov_b64 s[36:37], 0
	s_waitcnt lgkmcnt(0)
	s_load_dword s2, s[92:93], 0x30
	s_load_dword s3, s[92:93], 0x34
	s_waitcnt lgkmcnt(0)
	s_add_u32 s2, s2, s0
	s_addc_u32 s3, s3, 0
	s_and_b64 s[0:1], s[34:35], exec
	s_cselect_b32 s0, 0x400, 0
	s_load_dword s4, s[92:93], 0x28
	s_lshl_b32 s26, s0, 2
	s_load_dword s5, s[92:93], 0x2c
	s_waitcnt lgkmcnt(0)
	s_add_u32 s0, s4, s26
	s_addc_u32 s1, s5, 0
	s_cmpk_lt_u32 s10, 0x80
	v_mov_b32_e32 v0, v184
	s_cselect_b64 s[6:7], -1, 0
	s_cmpk_gt_u32 s10, 0x7f
	s_cbranch_scc1 .LBB0_511
	v_and_b32_e32 v1, 7, v0
	v_lshlrev_b32_e32 v128, 4, v1
	s_add_u32 s12, s24, 0x800000
	v_ashrrev_i32_e32 v20, 3, v0
	v_lshl_add_u64 v[2:3], s[2:3], 0, v[128:129]
	s_mov_b64 s[14:15], 0x3c80
	v_ashrrev_i32_e32 v22, 4, v0
	v_lshlrev_b32_e32 v0, 2, v0
	s_addc_u32 s13, s25, 0
	v_lshl_add_u64 v[16:17], v[2:3], 0, s[14:15]
	v_mul_u32_u24_e32 v1, 0x1010, v1
	v_lshlrev_b32_e32 v2, 2, v20
	s_movk_i32 s14, 0x404
	v_and_b32_e32 v0, 60, v0
	s_cmp_lg_u64 s[4:5], 0
	v_add3_u32 v21, 0, v1, v2
	v_mul_lo_u32 v1, v22, s14
	v_lshlrev_b32_e32 v2, 2, v0
	s_cselect_b64 s[20:21], -1, 0
	v_add3_u32 v23, 0, v1, v2
	s_lshl_b32 s14, s10, 8
	s_lshl_b32 s15, s51, 8
	v_lshlrev_b32_e32 v128, 1, v0
	s_mov_b32 s16, s10
	s_branch .LBB0_503

; __device__ __forceinline__ int tidx() { int t = threadIdx.x; asm volatile("" : "+v"(t)); return t; }
; #define INP(p, i) ldp((p).tbl, i)
; __device__ void conv_T(const float* __restrict__ src, int ld, int s0, int cnt, int K, const float* __restrict__ scale, bf16_t* __restrict__ dst, int d0, LAS unsigned char* lds, int vb, int nvb) {
;     LAS float* ts = (LAS float*)lds;
;     const int tid = tidx(); const int nkt = K / 256, ntile = (cnt / 32) * nkt;
;     if (vb < 0) return;
;     for (int tile = vb; tile < ntile; tile += nvb) {
;         const int n0 = (tile / nkt) * 32, k0 = (tile % nkt) * 256;
; __device__ void phase_convert_late(const Ctx& p, int l, LAS unsigned char* lds, int vb, int nvb) {
;     ...
;     conv_T(INP(p, 23) + (size_t)l * 512 * 1024, 1024, 0, 1024, 512, nullptr, (bf16_t*)(ws + OFF_WOA), 0, lds, vb, nvb);
.LBB0_523:
	v_mov_b64_e32 v[0:1], s[92:93]
	s_waitcnt vmcnt(0)
	s_and_b64 s[0:1], s[34:35], exec
	s_cselect_b32 s12, 0x80000, 0
	s_cmp_lt_u32 s10, 64
	v_mov_b32_e32 v5, v184
	s_cselect_b64 s[0:1], -1, 0
	s_cmp_gt_u32 s10, 63
	s_waitcnt lgkmcnt(0)
	s_load_dword s4, s[92:93], 0xbc
	s_load_dword s5, s[92:93], 0xb8
	s_waitcnt lgkmcnt(0)
	s_cbranch_scc1 .LBB0_526
	s_add_u32 s2, s24, 0xc00000
	v_ashrrev_i32_e32 v2, 3, v5
	v_and_b32_e32 v3, 7, v5
	s_addc_u32 s3, s25, 0
	s_lshl_b32 s6, s12, 2
	v_lshlrev_b32_e32 v128, 4, v3
	v_mul_u32_u24_e32 v3, 0x1010, v3
	v_lshlrev_b32_e32 v4, 2, v2
	s_add_u32 s6, s5, s6
	v_add3_u32 v3, 0, v3, v4
	v_ashrrev_i32_e32 v4, 4, v5
	v_lshlrev_b32_e32 v5, 2, v5
	s_addc_u32 s7, s4, 0
	s_movk_i32 s4, 0x404
	v_and_b32_e32 v6, 60, v5
	v_mul_lo_u32 v7, v4, s4
	v_lshlrev_b32_e32 v5, 2, v6
	v_lshl_add_u64 v[0:1], s[6:7], 0, v[128:129]
	v_add3_u32 v5, 0, v7, v5
	s_lshl_b32 s13, s10, 8
	s_lshl_b32 s20, s51, 8
	v_lshlrev_b32_e32 v128, 1, v6
	s_mov_b32 s21, s10

; __device__ __forceinline__ int tidx() { int t = threadIdx.x; asm volatile("" : "+v"(t)); return t; }
; #define INP(p, i) ldp((p).tbl, i)
; __device__ void conv_T(const float* __restrict__ src, int ld, int s0, int cnt, int K, const float* __restrict__ scale, bf16_t* __restrict__ dst, int d0, LAS unsigned char* lds, int vb, int nvb) {
;     LAS float* ts = (LAS float*)lds;
;     const int tid = tidx(); const int nkt = K / 256, ntile = (cnt / 32) * nkt;
;     if (vb < 0) return;
;     for (int tile = vb; tile < ntile; tile += nvb) {
;         const int n0 = (tile / nkt) * 32, k0 = (tile % nkt) * 256;
; __device__ void phase_convert_late(const Ctx& p, int l, LAS unsigned char* lds, int vb, int nvb) {
;     ...
;     conv_T(INP(p, 24) + (size_t)l * 512 * 1024, 1024, 0, 1024, 512, nullptr, (bf16_t*)(ws + OFF_WOB), 0, lds, vb, nvb);
.LBB0_526:
	v_mov_b64_e32 v[0:1], s[92:93]
	s_waitcnt vmcnt(0)
	v_mov_b32_e32 v5, v184
	s_andn2_b64 vcc, exec, s[0:1]
	s_waitcnt lgkmcnt(0)
	s_load_dword s2, s[92:93], 0xc4
	s_load_dword s3, s[92:93], 0xc0
	s_waitcnt lgkmcnt(0)
	s_cbranch_vccnz .LBB0_529
	s_add_u32 s0, s24, 0xd00000
	v_ashrrev_i32_e32 v2, 3, v5
	v_and_b32_e32 v3, 7, v5
	s_addc_u32 s1, s25, 0
	s_lshl_b32 s4, s12, 2
	v_lshlrev_b32_e32 v128, 4, v3
	v_mul_u32_u24_e32 v3, 0x1010, v3
	v_lshlrev_b32_e32 v4, 2, v2
	s_add_u32 s4, s3, s4
	v_add3_u32 v3, 0, v3, v4
	v_ashrrev_i32_e32 v4, 4, v5
	v_lshlrev_b32_e32 v5, 2, v5
	s_addc_u32 s5, s2, 0
	s_movk_i32 s2, 0x404
	v_and_b32_e32 v6, 60, v5
	v_mul_lo_u32 v7, v4, s2
	v_lshlrev_b32_e32 v5, 2, v6
	v_lshl_add_u64 v[0:1], s[4:5], 0, v[128:129]
	v_add3_u32 v5, 0, v7, v5
	s_lshl_b32 s6, s10, 8
	s_lshl_b32 s7, s51, 8
	v_lshlrev_b32_e32 v128, 1, v6
	s_mov_b32 s12, s10

; __device__ __forceinline__ int tidx() { int t = threadIdx.x; asm volatile("" : "+v"(t)); return t; }
; #define INP(p, i) ldp((p).tbl, i)
; __device__ void conv_T(const float* __restrict__ src, int ld, int s0, int cnt, int K, const float* __restrict__ scale, bf16_t* __restrict__ dst, int d0, LAS unsigned char* lds, int vb, int nvb) {
;     LAS float* ts = (LAS float*)lds;
;     const int tid = tidx(); const int nkt = K / 256, ntile = (cnt / 32) * nkt;
;     if (vb < 0) return;
;     for (int tile = vb; tile < ntile; tile += nvb) {
;         const int n0 = (tile / nkt) * 32, k0 = (tile % nkt) * 256;
; __device__ void phase_convert_late(const Ctx& p, int l, LAS unsigned char* lds, int vb, int nvb) {
;     ...
;     conv_T(INP(p, 25) + (size_t)l * 1024 * 1024, 1024, 0, 1024, 1024, nullptr, (bf16_t*)(ws + OFF_WO), 0, lds, vb, nvb);
.LBB0_529:
	v_mov_b64_e32 v[0:1], s[92:93]
	s_waitcnt vmcnt(0)
	v_mov_b32_e32 v5, v184
	s_and_b64 vcc, exec, s[38:39]
	v_readlane_b32 s39, v242, 28
	s_mov_b32 s38, 0x1ffff
	s_waitcnt lgkmcnt(0)
	s_load_dword s2, s[92:93], 0xcc
	s_load_dword s3, s[92:93], 0xc8
	s_waitcnt lgkmcnt(0)
	s_cbranch_vccnz .LBB0_532
	s_add_u32 s0, s24, 0xe00000
	s_addc_u32 s1, s25, 0
	s_and_b64 s[4:5], s[34:35], exec
	v_ashrrev_i32_e32 v2, 3, v5
	v_and_b32_e32 v3, 7, v5
	s_cselect_b32 s4, 0x400000, 0
	v_lshlrev_b32_e32 v128, 4, v3
	v_mul_u32_u24_e32 v3, 0x1010, v3
	v_lshlrev_b32_e32 v4, 2, v2
	s_add_u32 s4, s3, s4
	v_add3_u32 v3, 0, v3, v4
	v_ashrrev_i32_e32 v4, 4, v5
	v_lshlrev_b32_e32 v5, 2, v5
	s_addc_u32 s5, s2, 0
	s_movk_i32 s2, 0x404
	v_and_b32_e32 v6, 60, v5
	v_mul_lo_u32 v7, v4, s2
	v_lshlrev_b32_e32 v5, 2, v6
	v_lshl_add_u64 v[0:1], s[4:5], 0, v[128:129]
	v_add3_u32 v5, 0, v7, v5
	s_lshl_b32 s6, s10, 8
	s_lshl_b32 s7, s51, 8
	v_lshlrev_b32_e32 v128, 1, v6
	s_mov_b32 s12, s10

; __device__ __forceinline__ int tidx() { int t = threadIdx.x; asm volatile("" : "+v"(t)); return t; }
; #define INP(p, i) ldp((p).tbl, i)
; __device__ void conv_T(const float* __restrict__ src, int ld, int s0, int cnt, int K, const float* __restrict__ scale, bf16_t* __restrict__ dst, int d0, LAS unsigned char* lds, int vb, int nvb) {
;     LAS float* ts = (LAS float*)lds;
;     const int tid = tidx(); const int nkt = K / 256, ntile = (cnt / 32) * nkt;
;     if (vb < 0) return;
;     for (int tile = vb; tile < ntile; tile += nvb) {
;         const int n0 = (tile / nkt) * 32, k0 = (tile % nkt) * 256;
; __device__ void phase_convert_late(const Ctx& p, int l, LAS unsigned char* lds, int vb, int nvb) {
;     ...
;     conv_T(INP(p, 27) + (size_t)l * 1024 * 4096, 4096, 0, 4096, 1024, INP(p, 26) + l * 1024, (bf16_t*)(ws + OFF_WUP), 0, lds, vb, nvb);
.LBB0_532:
	v_mov_b64_e32 v[0:1], s[92:93]
	s_waitcnt vmcnt(0)
	s_and_b64 s[0:1], s[34:35], exec
	s_waitcnt vmcnt(0)
	s_cselect_b32 s14, 0x1000000, 0
	s_cmpk_lt_u32 s10, 0x200
	s_cselect_b64 s[0:1], -1, 0
	s_cmpk_gt_u32 s10, 0x1ff
	s_waitcnt lgkmcnt(0)
	s_load_dword s12, s[92:93], 0xdc
	s_load_dword s13, s[92:93], 0xd8
	s_waitcnt lgkmcnt(0)
	s_load_dword s7, s[92:93], 0xd4
	s_load_dword s6, s[92:93], 0xd0
	s_waitcnt lgkmcnt(0)
	v_mov_b32_e32 v0, v184
	s_cbranch_scc1 .LBB0_544
	s_add_u32 s2, s6, s26
	s_addc_u32 s3, s7, 0
	s_add_u32 s4, s24, 0x1000000
	s_addc_u32 s5, s25, 0
	s_add_u32 s16, s13, s14
	v_ashrrev_i32_e32 v20, 3, v0
	v_and_b32_e32 v1, 7, v0
	v_ashrrev_i32_e32 v22, 4, v0
	v_lshlrev_b32_e32 v0, 2, v0
	s_addc_u32 s17, s12, 0
	v_lshlrev_b32_e32 v128, 4, v1
	v_mul_u32_u24_e32 v1, 0x1010, v1
	v_lshlrev_b32_e32 v2, 2, v20
	s_movk_i32 s12, 0x404
	v_and_b32_e32 v0, 60, v0
	s_cmp_lg_u64 s[6:7], 0
	v_add3_u32 v21, 0, v1, v2
	v_mul_lo_u32 v1, v22, s12
	v_lshlrev_b32_e32 v2, 2, v0
	v_lshl_add_u64 v[16:17], s[16:17], 0, v[128:129]
	s_cselect_b64 s[6:7], -1, 0
	v_add3_u32 v23, 0, v1, v2
	s_lshl_b32 s15, s10, 8
	s_lshl_b32 s16, s51, 8
	v_lshlrev_b32_e32 v128, 1, v0
	s_mov_b32 s17, s10
	s_branch .LBB0_535

; __device__ __forceinline__ int tidx() { int t = threadIdx.x; asm volatile("" : "+v"(t)); return t; }
; #define INP(p, i) ldp((p).tbl, i)
; __device__ void conv_T(const float* __restrict__ src, int ld, int s0, int cnt, int K, const float* __restrict__ scale, bf16_t* __restrict__ dst, int d0, LAS unsigned char* lds, int vb, int nvb) {
;     LAS float* ts = (LAS float*)lds;
;     const int tid = tidx(); const int nkt = K / 256, ntile = (cnt / 32) * nkt;
;     if (vb < 0) return;
;     for (int tile = vb; tile < ntile; tile += nvb) {
;         const int n0 = (tile / nkt) * 32, k0 = (tile % nkt) * 256;
; __device__ void phase_convert_late(const Ctx& p, int l, LAS unsigned char* lds, int vb, int nvb) {
;     ...
;     conv_T(INP(p, 28) + (size_t)l * 4096 * 1024, 1024, 0, 1024, 4096, nullptr, (bf16_t*)(ws + OFF_WDN), 0, lds, vb, nvb);
.LBB0_544:
	v_mov_b64_e32 v[0:1], s[92:93]
	s_waitcnt vmcnt(0)
	v_mov_b32_e32 v5, v184
	s_andn2_b64 vcc, exec, s[0:1]
	s_waitcnt lgkmcnt(0)
	s_load_dword s2, s[92:93], 0xe4
	s_load_dword s3, s[92:93], 0xe0
	s_waitcnt lgkmcnt(0)
	s_cbranch_vccnz .LBB0_547
	s_add_u32 s0, s24, 0x1800000
	v_ashrrev_i32_e32 v2, 3, v5
	v_and_b32_e32 v3, 7, v5
	s_addc_u32 s1, s25, 0
	v_lshlrev_b32_e32 v128, 4, v3
	v_mul_u32_u24_e32 v3, 0x1010, v3
	v_lshlrev_b32_e32 v4, 2, v2
	s_add_u32 s4, s3, s14
	v_add3_u32 v3, 0, v3, v4
	v_ashrrev_i32_e32 v4, 4, v5
	v_lshlrev_b32_e32 v5, 2, v5
	s_addc_u32 s5, s2, 0
	s_movk_i32 s2, 0x404
	v_and_b32_e32 v6, 60, v5
	v_mul_lo_u32 v7, v4, s2
	v_lshlrev_b32_e32 v5, 2, v6
	v_lshl_add_u64 v[0:1], s[4:5], 0, v[128:129]
	v_add3_u32 v5, 0, v7, v5
	s_lshl_b32 s6, s10, 8
	s_lshl_b32 s7, s51, 8
	v_lshlrev_b32_e32 v128, 1, v6

; __device__ __forceinline__ int tidx() { int t = threadIdx.x; asm volatile("" : "+v"(t)); return t; }
; __device__ __forceinline__ int bidx() { int b = blockIdx.x; asm volatile("" : "+s"(b)); return b; }
; #define INP(p, i) ldp((p).tbl, i)
; __device__ void phase_rwkv_fix(const Ctx& p, int l) {
;     unsigned char* ws = uptr(p.ws);
;     const bf16_t* YH = (const bf16_t*)(ws + OFF_A); const bf16_t* QH = (const bf16_t*)(ws + OFF_A + SLOT); const float* UC = (const float*)(ws + OFF_A + 50 * MiB);
;     const bf16_t* V = (const bf16_t*)(l == 0 ? ws + OFF_V0 : ws + OFF_B + SLOT); const bf16_t* G = (const bf16_t*)(ws + OFF_G); const float* bonus = (const float*)(ws + OFF_SM + SM_BONUS);
;     bf16_t* YA = (bf16_t*)(ws + OFF_B);
;     const int tid = tidx(); const int wave = __builtin_amdgcn_readfirstlane(tid >> 6), lane = tid & 63, fr = lane & 15, fq = lane >> 4;
;     const float* lnw = INP(p, 19) + l * 512; const float* lnb = INP(p, 20) + l * 512;
;     for (int item = bidx() * 8 + wave; item < 4096 + 256; item += gridDim.x * 8) {
; __global__ void __launch_bounds__(512, 2) mega_fwd(Params prm) {
;     ...
;         switch (k) {
.LBB0_548:
	s_and_b64 vcc, exec, s[0:1]
	s_cbranch_vccz .LBB0_1163
	s_cmp_gt_i32 s65, 2
	s_mov_b64 s[0:1], -1
	s_cbranch_scc0 .LBB0_601
	s_cmp_lt_i32 s65, 4
	s_cbranch_scc1 .LBB0_582
	s_cmp_gt_i32 s65, 4
	s_cbranch_scc0 .LBB0_570
	s_mov_b32 s0, s86
	s_mov_b32 s1, s87
	v_mov_b32_e32 v0, v184
	v_mov_b64_e32 v[2:3], s[92:93]
	s_waitcnt lgkmcnt(0)
	s_waitcnt vmcnt(0)
	s_waitcnt vmcnt(0)
	s_mov_b32 s2, s90
	v_readfirstlane_b32 s3, v0
	s_lshl_b32 s4, s2, 3
	s_ashr_i32 s3, s3, 6
	s_add_i32 s12, s4, s3
	s_cmpk_gt_i32 s12, 0x10ff
	s_waitcnt lgkmcnt(0)
	s_load_dword s4, s[92:93], 0x9c
	s_load_dword s5, s[92:93], 0x98
	s_waitcnt lgkmcnt(0)
	s_load_dword s6, s[92:93], 0xa4
	s_load_dword s7, s[92:93], 0xa0
	s_waitcnt lgkmcnt(0)
	s_cbranch_scc1 .LBB0_569
	s_add_u32 s13, s0, 0x20c0000
	s_addc_u32 s20, s1, 0
	s_and_b64 s[14:15], s[34:35], exec
	s_cselect_b32 s10, 0x800, 0
	s_add_u32 s14, s7, s10
	s_addc_u32 s15, s6, 0
	s_add_u32 s6, s5, s10
	s_addc_u32 s7, s4, 0
	s_and_b64 s[4:5], s[34:35], exec
	s_mov_b32 s4, 0xaa00000
	s_cselect_b32 s4, s4, 0x4400000
	v_bfe_u32 v2, v0, 4, 2
	s_add_u32 s4, s0, s4
	v_lshlrev_b32_e32 v128, 3, v2
	s_addc_u32 s5, s1, 0
	v_and_b32_e32 v7, 64, v189
	v_and_b32_e32 v139, 15, v0
	v_lshlrev_b32_e32 v0, 5, v2
	v_mov_b32_e32 v1, v129
	v_lshl_add_u64 v[4:5], s[0:1], 0, v[128:129]
	v_lshl_add_u64 v[70:71], s[4:5], 0, v[128:129]
	s_mov_b64 s[4:5], 0x800000
	v_xor_b32_e32 v6, 16, v189
	v_add_u32_e32 v7, 64, v7
	v_lshl_add_u64 v[0:1], s[0:1], 0, v[0:1]
	v_lshl_add_u64 v[72:73], v[4:5], 0, s[4:5]
	v_cmp_lt_i32_e32 vcc, v6, v7
	s_mov_b64 s[4:5], 0x9900000
	v_lshlrev_b32_e32 v128, 8, v139
	v_lshlrev_b32_e32 v2, 4, v2
	v_mov_b32_e32 v3, v129
	v_cndmask_b32_e32 v6, v189, v6, vcc
	v_lshl_add_u64 v[74:75], v[4:5], 0, s[4:5]
	v_lshl_add_u64 v[0:1], v[0:1], 0, v[128:129]
	s_mov_b64 s[4:5], 0x8700000
	v_lshlrev_b32_e32 v154, 2, v6
	v_xor_b32_e32 v6, 32, v189
	v_lshl_add_u64 v[76:77], v[0:1], 0, s[4:5]
	v_lshl_add_u64 v[0:1], s[0:1], 0, v[2:3]
	s_mov_b64 s[0:1], 0x6600000
	v_cmp_lt_i32_e32 vcc, v6, v7
	v_lshl_add_u64 v[78:79], v[0:1], 0, s[0:1]
	s_lshl_b32 s0, s2, 5
	s_lshl_b32 s1, s3, 2
	v_lshl_add_u64 v[64:65], s[6:7], 0, v[2:3]
	s_mov_b64 s[6:7], 0x5500000
	v_cndmask_b32_e32 v6, v189, v6, vcc
	s_add_i32 s21, s0, s1
	s_lshl_b32 s0, s2, 8
	s_lshl_b32 s1, s3, 5
	v_lshl_add_u64 v[66:67], s[14:15], 0, v[2:3]
	v_lshl_add_u64 v[68:69], v[4:5], 0, s[6:7]
	v_lshlrev_b32_e32 v155, 2, v6
	s_add_i32 s22, s0, s1
	s_branch .LBB0_555

; __device__ __forceinline__ int bidx() { int b = blockIdx.x; asm volatile("" : "+s"(b)); return b; }
; #define INP(p, i) ldp((p).tbl, i)
; __device__ __forceinline__ float bf2f(unsigned short b) { return __uint_as_float((unsigned)b << 16); }
; __device__ __forceinline__ f2 pfma(f2 a, f2 b, f2 c) { return __builtin_elementwise_fma(a, b, c); }
; template <bool ID> __device__ __forceinline__ void rwkv_scan(const bf16_t* __restrict__ R, const bf16_t* __restrict__ EW, const bf16_t* __restrict__ K, const bf16_t* __restrict__ V, ...
;     unsigned short q1[6], q2[6];
;     { unsigned o = base; q1[0] = R[o]; q1[1] = EW[o]; q1[2] = K[o]; q1[3] = V[o]; q1[4] = A[o]; q1[5] = B[o];
;       o = base + 512u; q2[0] = R[o]; q2[1] = EW[o]; q2[2] = K[o]; q2[3] = V[o]; q2[4] = A[o]; q2[5] = B[o]; }
;     const LAS f32x4* pa = (const LAS f32x4*)L;
;     float sav, sai;
;     { L[lane] = bf2f(q1[4]);
;       f2 av = {0.f, 0.f}, ai = {0.f, 0.f};
; #pragma unroll
;       for (int q = 0; q < 16; ++q) { const f32x4 a4 = pa[q]; const f2 a01 = {a4[0], a4[1]}, a23 = {a4[2], a4[3]};
;           av = pfma(Sv[2 * q], a01, av); av = pfma(Sv[2 * q + 1], a23, av); if (ID) { ai = pfma(Si[2 * q], a01, ai); ai = pfma(Si[2 * q + 1], a23, ai); } }
;       sav = av[0] + av[1]; sai = ai[0] + ai[1]; }
; __device__ void phase_rwkv_scan(const Ctx& p, int l, LAS unsigned char* lds) {
;     ...
;     } else if (wave == 4) {
;         for (int item = bidx(); item < 256; item += gridDim.x) {
;             const int s = item >> 3, h = item & 7;
;             const size_t so = (((size_t)l * 32 + s) * 8 + h) * 4096 + lane * 64;
;             f2 Sv[32], Si[32];
;             const float* sp = INP(p, 3) + so;
; #pragma unroll
;             for (int i = 0; i < 32; i += 2) { const float4 q = *(const float4*)(sp + 2 * i); Sv[i] = (f2){q.x, q.y}; Sv[i + 1] = (f2){q.z, q.w}; Si[i] = (f2){0.f, 0.f}; Si[i + 1] = (f2){0.f, 0.f}; }
;             rwkv_scan<false>(R, EW, K, V, A, B, (unsigned)((T_P + s * 32) * 512 + h * 64 + lane), 32, Sv, Si, YH, QH, L, lane);
.Lscan_s:
	v_lshrrev_b32_e32 v78, 5, v139
	v_and_b32_e32 v79, 31, v139
	s_mov_b32 s26, -1
	s_mov_b32 s27, 0
	v_mov_b64_e32 v[0:1], s[92:93]
	s_waitcnt vmcnt(0) lgkmcnt(0)
	s_load_dword s14, s[92:93], 0x18
	s_load_dword s15, s[92:93], 0x1c
	s_waitcnt lgkmcnt(0)
	s_and_b64 s[36:37], s[34:35], exec
	s_cselect_b32 s36, 32, 0
	s_lshr_b32 s37, s90, 3
	s_add_i32 s36, s36, s37
	s_lshl_b32 s36, s36, 17
	s_and_b32 s37, s90, 7
	s_lshl_b32 s37, s37, 14
	s_or_b32 s36, s36, s37
	s_add_u32 s16, s14, s36
	s_addc_u32 s17, s15, 0
	v_readlane_b32 s14, v242, 1
	v_readlane_b32 s15, v242, 2
	s_add_u32 s36, s14, s36
	s_addc_u32 s37, s15, 0
	s_lshr_b32 s14, s90, 3
	s_lshl_b32 s14, s14, 14
	s_and_b32 s15, s90, 7
	s_lshl_b32 s15, s15, 6
	s_or_b32 s14, s14, s15
	s_add_i32 s14, s14, 0x800000
	v_add_lshl_u32 v72, s14, v139, 1
	v_add_lshl_u32 v81, s14, v79, 1
	v_mov_b32_e32 v74, s20
	v_mov_b32_e32 v75, s21
	v_mov_b32_e32 v80, s6
	v_cndmask_b32_e64 v74, v80, v74, s[26:27]
	v_mov_b32_e32 v80, s7
	v_cndmask_b32_e64 v75, v80, v75, s[26:27]
	v_add_co_u32_e32 v74, vcc, v74, v81
	s_nop 1
	v_addc_co_u32_e32 v75, vcc, 0, v75, vcc
	v_lshl_add_u32 v76, v78, 4, s10
	v_lshl_add_u32 v77, v139, 2, s10
	v_lshl_add_u32 v251, v79, 2, s10
	v_mov_b32_e32 v246, 1.0
	v_lshlrev_b32_e32 v81, 2, v78
	v_sub_u32_e32 v81, v79, v81
	global_load_ushort v254, v72, s[12:13]
	global_load_ushort v224, v72, s[4:5] offset:0
	global_load_ushort v225, v72, s[0:1] offset:0
	global_load_ushort v226, v72, s[12:13] offset:1024
	global_load_ushort v227, v[74:75], off offset:0
	global_load_ushort v228, v[74:75], off offset:64
	global_load_ushort v229, v72, s[2:3] offset:0
	global_load_ushort v230, v72, s[4:5] offset:1024
	global_load_ushort v231, v72, s[0:1] offset:1024
	global_load_ushort v232, v72, s[12:13] offset:2048
	global_load_ushort v233, v[74:75], off offset:1024
	global_load_ushort v234, v[74:75], off offset:1088
	global_load_ushort v235, v72, s[2:3] offset:1024
	global_load_ushort v82, v72, s[4:5] offset:2048
	global_load_ushort v83, v72, s[0:1] offset:2048
	global_load_ushort v84, v72, s[12:13] offset:3072
	global_load_ushort v85, v[74:75], off offset:2048
	global_load_ushort v86, v[74:75], off offset:2112
	global_load_ushort v87, v72, s[2:3] offset:2048
	v_add_u32_e32 v72, 0xc00, v72
	v_lshl_add_u64 v[74:75], v[74:75], 0, s[54:55]
	v_lshl_add_u64 v[74:75], v[74:75], 0, s[54:55]
	v_lshl_add_u64 v[74:75], v[74:75], 0, s[54:55]
	global_load_ushort v88, v72, s[4:5] offset:0
	global_load_ushort v89, v72, s[0:1] offset:0
	global_load_ushort v90, v72, s[12:13] offset:1024
	global_load_ushort v91, v[74:75], off offset:0
	global_load_ushort v92, v[74:75], off offset:64
	global_load_ushort v93, v72, s[2:3] offset:0
	v_add_u32_e32 v72, 0x400, v72
	v_lshl_add_u64 v[74:75], v[74:75], 0, s[54:55]
	v_lshlrev_b32_e32 v252, 8, v79
	v_lshl_add_u32 v252, v78, 4, v252
	v_add_u32_e32 v253, 0x2000, v252
	global_load_dwordx4 v[0:3], v252, s[16:17] offset:0
	global_load_dwordx4 v[4:7], v252, s[16:17] offset:32
	global_load_dwordx4 v[8:11], v252, s[16:17] offset:64
	global_load_dwordx4 v[12:15], v252, s[16:17] offset:96
	global_load_dwordx4 v[16:19], v252, s[16:17] offset:128
	global_load_dwordx4 v[20:23], v252, s[16:17] offset:160
	global_load_dwordx4 v[24:27], v252, s[16:17] offset:192
	global_load_dwordx4 v[28:31], v252, s[16:17] offset:224
	global_load_dwordx4 v[32:35], v253, s[16:17] offset:0
	global_load_dwordx4 v[36:39], v253, s[16:17] offset:32
	global_load_dwordx4 v[40:43], v253, s[16:17] offset:64
	global_load_dwordx4 v[44:47], v253, s[16:17] offset:96
	global_load_dwordx4 v[48:51], v253, s[16:17] offset:128
	global_load_dwordx4 v[52:55], v253, s[16:17] offset:160
	global_load_dwordx4 v[56:59], v253, s[16:17] offset:192
	global_load_dwordx4 v[60:63], v253, s[16:17] offset:224
	s_waitcnt vmcnt(0)
	v_lshlrev_b32_e32 v254, 16, v254
	ds_write_b32 v77, v254 offset:1280
	ds_write_b32 v77, v254 offset:1024
	ds_read_b128 v[148:151], v76 offset:1024
	ds_read_b128 v[152:155], v76 offset:1056
	ds_read_b128 v[156:159], v76 offset:1088
	ds_read_b128 v[160:163], v76 offset:1120
	ds_read_b128 v[164:167], v76 offset:1280
	ds_read_b128 v[168:171], v76 offset:1312
	ds_read_b128 v[172:175], v76 offset:1344
	ds_read_b128 v[176:179], v76 offset:1376
	ds_read_b128 v[192:195], v76 offset:1152
	ds_read_b128 v[196:199], v76 offset:1184
	ds_read_b128 v[200:203], v76 offset:1216
	ds_read_b128 v[204:207], v76 offset:1248
	ds_read_b128 v[208:211], v76 offset:1408
	ds_read_b128 v[212:215], v76 offset:1440
	ds_read_b128 v[216:219], v76 offset:1472
	ds_read_b128 v[220:223], v76 offset:1504
	s_waitcnt lgkmcnt(8)
; __device__ __forceinline__ float bf2f(unsigned short b) { return __uint_as_float((unsigned)b << 16); }
; __device__ __forceinline__ f2 pfma(f2 a, f2 b, f2 c) { return __builtin_elementwise_fma(a, b, c); }
; template <bool ID> __device__ __forceinline__ void rwkv_scan(const bf16_t* __restrict__ R, const bf16_t* __restrict__ EW, const bf16_t* __restrict__ K, const bf16_t* __restrict__ V, ...
;     ...
;     { L[lane] = bf2f(q1[4]);
;       f2 av = {0.f, 0.f}, ai = {0.f, 0.f};
; #pragma unroll
;       for (int q = 0; q < 16; ++q) { const f32x4 a4 = pa[q]; const f2 a01 = {a4[0], a4[1]}, a23 = {a4[2], a4[3]};
;           av = pfma(Sv[2 * q], a01, av); av = pfma(Sv[2 * q + 1], a23, av); if (ID) { ai = pfma(Si[2 * q], a01, ai); ai = pfma(Si[2 * q + 1], a23, ai); } }
;       sav = av[0] + av[1]; sai = ai[0] + ai[1]; }
;     ...
;         L[lane] = bf2f(q2[4]); L[64 + lane] = __expf(-bf2f(q1[1])); L[128 + lane] = bf2f(q1[5]); L[192 + lane] = bf2f(q1[2]); L[256 + lane] = bf2f(q1[0]);
	v_pk_mul_f32 v[64:65], v[0:1], v[148:149]
	v_pk_mul_f32 v[68:69], v[0:1], v[164:165]
	v_pk_fma_f32 v[64:65], v[2:3], v[150:151], v[64:65]
	v_pk_fma_f32 v[68:69], v[2:3], v[166:167], v[68:69]
	v_pk_fma_f32 v[64:65], v[4:5], v[152:153], v[64:65]
	v_pk_fma_f32 v[68:69], v[4:5], v[168:169], v[68:69]
	v_pk_fma_f32 v[64:65], v[6:7], v[154:155], v[64:65]
	v_pk_fma_f32 v[68:69], v[6:7], v[170:171], v[68:69]
	v_pk_fma_f32 v[64:65], v[8:9], v[156:157], v[64:65]
	v_pk_fma_f32 v[68:69], v[8:9], v[172:173], v[68:69]
	v_pk_fma_f32 v[64:65], v[10:11], v[158:159], v[64:65]
	v_pk_fma_f32 v[68:69], v[10:11], v[174:175], v[68:69]
	v_pk_fma_f32 v[64:65], v[12:13], v[160:161], v[64:65]
	v_pk_fma_f32 v[68:69], v[12:13], v[176:177], v[68:69]
	v_pk_fma_f32 v[64:65], v[14:15], v[162:163], v[64:65]
	v_pk_fma_f32 v[68:69], v[14:15], v[178:179], v[68:69]
	v_pk_mul_f32 v[66:67], v[32:33], v[148:149]
	v_pk_mul_f32 v[70:71], v[32:33], v[164:165]
	v_pk_fma_f32 v[66:67], v[34:35], v[150:151], v[66:67]
	v_pk_fma_f32 v[70:71], v[34:35], v[166:167], v[70:71]
	v_pk_fma_f32 v[66:67], v[36:37], v[152:153], v[66:67]
	v_pk_fma_f32 v[70:71], v[36:37], v[168:169], v[70:71]
	v_pk_fma_f32 v[66:67], v[38:39], v[154:155], v[66:67]
	v_pk_fma_f32 v[70:71], v[38:39], v[170:171], v[70:71]
	v_pk_fma_f32 v[66:67], v[40:41], v[156:157], v[66:67]
	v_pk_fma_f32 v[70:71], v[40:41], v[172:173], v[70:71]
	v_pk_fma_f32 v[66:67], v[42:43], v[158:159], v[66:67]
	v_pk_fma_f32 v[70:71], v[42:43], v[174:175], v[70:71]
	v_pk_fma_f32 v[66:67], v[44:45], v[160:161], v[66:67]
	v_pk_fma_f32 v[70:71], v[44:45], v[176:177], v[70:71]
	v_pk_fma_f32 v[66:67], v[46:47], v[162:163], v[66:67]
	v_pk_fma_f32 v[70:71], v[46:47], v[178:179], v[70:71]
	s_waitcnt lgkmcnt(0)
	v_pk_fma_f32 v[64:65], v[16:17], v[192:193], v[64:65]
	v_pk_fma_f32 v[68:69], v[16:17], v[208:209], v[68:69]
	v_pk_fma_f32 v[64:65], v[18:19], v[194:195], v[64:65]
	v_pk_fma_f32 v[68:69], v[18:19], v[210:211], v[68:69]
	v_pk_fma_f32 v[64:65], v[20:21], v[196:197], v[64:65]
	v_pk_fma_f32 v[68:69], v[20:21], v[212:213], v[68:69]
	v_pk_fma_f32 v[64:65], v[22:23], v[198:199], v[64:65]
	v_pk_fma_f32 v[68:69], v[22:23], v[214:215], v[68:69]
	v_pk_fma_f32 v[64:65], v[24:25], v[200:201], v[64:65]
	v_pk_fma_f32 v[68:69], v[24:25], v[216:217], v[68:69]
	v_pk_fma_f32 v[64:65], v[26:27], v[202:203], v[64:65]
	v_pk_fma_f32 v[68:69], v[26:27], v[218:219], v[68:69]
	v_pk_fma_f32 v[64:65], v[28:29], v[204:205], v[64:65]
	v_pk_fma_f32 v[68:69], v[28:29], v[220:221], v[68:69]
	v_pk_fma_f32 v[64:65], v[30:31], v[206:207], v[64:65]
	v_pk_fma_f32 v[68:69], v[30:31], v[222:223], v[68:69]
	v_pk_fma_f32 v[66:67], v[48:49], v[192:193], v[66:67]
	v_pk_fma_f32 v[70:71], v[48:49], v[208:209], v[70:71]
	v_pk_fma_f32 v[66:67], v[50:51], v[194:195], v[66:67]
	v_pk_fma_f32 v[70:71], v[50:51], v[210:211], v[70:71]
	v_pk_fma_f32 v[66:67], v[52:53], v[196:197], v[66:67]
	v_pk_fma_f32 v[70:71], v[52:53], v[212:213], v[70:71]
	v_pk_fma_f32 v[66:67], v[54:55], v[198:199], v[66:67]
	v_pk_fma_f32 v[70:71], v[54:55], v[214:215], v[70:71]
	v_pk_fma_f32 v[66:67], v[56:57], v[200:201], v[66:67]
	v_pk_fma_f32 v[70:71], v[56:57], v[216:217], v[70:71]
	v_pk_fma_f32 v[66:67], v[58:59], v[202:203], v[66:67]
	v_pk_fma_f32 v[70:71], v[58:59], v[218:219], v[70:71]
	v_pk_fma_f32 v[66:67], v[60:61], v[204:205], v[66:67]
	v_pk_fma_f32 v[70:71], v[60:61], v[220:221], v[70:71]
	v_pk_fma_f32 v[66:67], v[62:63], v[206:207], v[66:67]
	v_pk_fma_f32 v[70:71], v[62:63], v[222:223], v[70:71]
	v_add_f32_e32 v68, v68, v69
	v_add_f32_e32 v70, v70, v71
	s_nop 0
	s_nop 0
	v_permlane32_swap_b32_e32 v68, v70
	v_add_f32_e32 v255, v68, v70
	v_lshlrev_b32_e32 v78, 16, v224
	v_mul_f32_e32 v78, 0xbfb8aa3b, v78
	v_exp_f32_e32 v78, v78
	v_lshlrev_b32_e32 v79, 16, v225
	v_lshlrev_b32_e32 v80, 16, v226
	v_mul_f32_e32 v246, v246, v78
	v_mul_f32_e32 v79, v79, v246
	v_mul_f32_e32 v80, v80, v246
	v_rcp_f32_e32 v248, v246
	s_nop 0
	ds_write2st64_b32 v77, v248, v79 offset0:0 offset1:1
	ds_write_b32 v77, v80 offset:512
	ds_read_b32 v249, v251 offset:0
	ds_read_b32 v250, v251 offset:128
	v_lshlrev_b32_e32 v240, 16, v227
	v_lshlrev_b32_e32 v241, 16, v228
	s_waitcnt lgkmcnt(0)
	v_mul_f32_e32 v240, v240, v249
	v_mul_f32_e32 v241, v241, v250
	v_mov_b32_e32 v244, v255
	v_lshlrev_b32_e32 v245, 16, v229
	s_nop 0
	s_nop 0
	v_permlane32_swap_b32_e32 v244, v245
	s_movk_i32 s41, 0

; __device__ __forceinline__ int tidx() { int t = threadIdx.x; asm volatile("" : "+v"(t)); return t; }
; #define INP(p, i) ldp((p).tbl, i)
; __device__ void phase_prep(const Ctx& p, int l, LAS unsigned char* lds) {
;     constexpr int MXS = 1832, MIDS = 40;
;     unsigned char* ws = uptr(p.ws);
;     const bf16_t* PR = (const bf16_t*)(ws + OFF_A);
;     LAS bf16_t* MX = (LAS bf16_t*)lds; LAS bf16_t* MID = (LAS bf16_t*)(lds + 32 * MXS * 2);
;     const int tid = tidx(); const int wave = __builtin_amdgcn_readfirstlane(tid >> 6), lane = tid & 63, fr = lane & 15, fq = lane >> 4;
;     const float* mu = INP(p, 7) + l * 1824;
;     const bf16_t* w2T = (const bf16_t*)(ws + OFF_SM + SM_W2T); const bf16_t* a2T = (const bf16_t*)(ws + OFF_SM + SM_A2T); const bf16_t* g2T = (const bf16_t*)(ws + OFF_SM + SM_G2T);
;     const bf16_t* v1T = (const bf16_t*)(ws + OFF_SM + SM_V1T); const bf16_t* v2T = (const bf16_t*)(ws + OFF_SM + SM_V2T);
;     bf16_t* oR = (bf16_t*)(ws + OFF_B); bf16_t* oV = (bf16_t*)(l == 0 ? ws + OFF_V0 : ws + OFF_B + SLOT); bf16_t* oE = (bf16_t*)(ws + OFF_B + 2 * SLOT);
;     bf16_t* oK = (bf16_t*)(ws + OFF_B + 3 * SLOT); bf16_t* oA = (bf16_t*)(ws + OFF_B + 4 * SLOT); bf16_t* oB = (bf16_t*)(ws + OFF_B + 5 * SLOT);
;     bf16_t* oG = (bf16_t*)(ws + OFF_G); const bf16_t* V0 = (const bf16_t*)(ws + OFF_V0);
;     float* bonus = (float*)(ws + OFF_SM + SM_BONUS);
;     const float* w0 = INP(p, 8) + l * 512; const float* a0 = INP(p, 10) + l * 512; const float* kkp = INP(p, 16) + l * 512; const float* kap = INP(p, 17) + l * 512; const float* rkp = INP(p, 18) + l * 512;
;     const float* v0p = INP(p, 13);
.LBB0_601:
	s_andn2_b64 vcc, exec, s[0:1]
	s_mov_b64 s[36:37], 0
	s_cbranch_vccnz .LBB0_1163
	s_cmp_gt_i32 s65, 0
	s_mov_b64 s[2:3], -1
	s_cbranch_scc0 .LBB0_1365
	s_cmp_gt_i32 s65, 1
	s_cbranch_scc0 .LBB0_1332
	s_mov_b32 s46, s86
	s_mov_b32 s47, s87
	v_mov_b32_e32 v0, v184
	v_mov_b64_e32 v[2:3], s[92:93]
	s_waitcnt lgkmcnt(0)
	s_waitcnt vmcnt(0)
	s_mov_b32 s53, s90
	s_mov_b32 s79, s65
	s_movk_i32 s58, 0xa0
	v_readfirstlane_b32 s10, v0
	s_mov_b64 s[0:1], s[88:89]
	s_movk_i32 s75, 0xe50
	s_waitcnt lgkmcnt(0)
	s_load_dword s14, s[92:93], 0x3c
	s_load_dword s15, s[92:93], 0x38
	s_waitcnt lgkmcnt(0)
	s_waitcnt vmcnt(0) lgkmcnt(0)
	s_load_dword s2, s[92:93], 0x44
	s_load_dword s3, s[92:93], 0x40
	s_waitcnt lgkmcnt(0)
	s_waitcnt vmcnt(0) lgkmcnt(0)
	s_load_dword s16, s[92:93], 0x54
	s_load_dword s17, s[92:93], 0x50
	s_waitcnt lgkmcnt(0)
	s_waitcnt vmcnt(0) lgkmcnt(0)
	s_load_dword s29, s[92:93], 0x84
	s_load_dword s38, s[92:93], 0x80
	s_waitcnt lgkmcnt(0)
	s_waitcnt vmcnt(0) lgkmcnt(0)
	s_load_dword s39, s[92:93], 0x8c
	s_load_dword s40, s[92:93], 0x88
	s_waitcnt lgkmcnt(0)
	s_waitcnt vmcnt(0) lgkmcnt(0)
	s_load_dword s41, s[92:93], 0x94
	s_waitcnt vmcnt(0)
	s_load_dword s42, s[92:93], 0x90
	s_waitcnt lgkmcnt(0)
	s_cmpk_gt_i32 s53, 0x21f
	s_waitcnt lgkmcnt(0)
	s_load_dword s5, s[92:93], 0x6c
	s_load_dword s4, s[92:93], 0x68
	s_waitcnt lgkmcnt(0)
	s_cbranch_scc1 .LBB0_1314
	s_add_u32 s6, s46, 0x9900000
	s_addc_u32 s7, s47, 0
	s_add_u32 s12, s46, 0xbb00000
	s_addc_u32 s13, s47, 0
	s_add_u32 s20, s46, 0xcc00000
	s_addc_u32 s21, s47, 0
	s_add_u32 s22, s46, 0xdd00000
	s_addc_u32 s23, s47, 0
	s_add_u32 s24, s46, 0xee00000
	s_addc_u32 s25, s47, 0
	s_add_u32 s26, s46, 0x800000
	s_addc_u32 s27, s47, 0
	s_add_u32 s30, s46, 0x4400000
	s_addc_u32 s31, s47, 0
	s_and_b64 s[0:1], s[34:35], exec
	s_cselect_b32 s0, 0x800, 0
	s_add_u32 s36, s3, s0
	s_addc_u32 s37, s2, 0
	s_add_u32 s48, s17, s0
	s_addc_u32 s49, s16, 0
	s_add_u32 s56, s38, s0
	s_addc_u32 s57, s29, 0
	s_add_u32 s2, s40, s0
	s_addc_u32 s3, s39, 0
	s_add_u32 s96, s42, s0
	s_addc_u32 s97, s41, 0
	s_and_b64 s[0:1], s[34:35], exec
	s_mov_b32 s0, 0xaa00000
	s_cselect_b32 s16, s0, 0x4400000
	s_cselect_b32 s0, 0x1c80, 0
	s_add_u32 s0, s15, s0
	s_movk_i32 s15, 0x1c8
	v_cmp_gt_i32_e64 s[38:39], s15, v0
	s_mov_b32 s15, 0x8fb823ef
	v_mul_hi_i32 v1, v0, s15
	v_add_u32_e32 v1, v1, v0
	v_lshrrev_b32_e32 v2, 31, v1
	v_ashrrev_i32_e32 v1, 7, v1
	v_add_u32_e32 v1, v1, v2
	s_movk_i32 s15, 0xe4
	v_mul_lo_u32 v2, v1, s15
	v_sub_u32_e32 v5, v0, v2
	v_lshlrev_b32_e32 v84, 3, v5
	s_addc_u32 s1, s14, 0
	v_ashrrev_i32_e32 v85, 31, v84
	v_lshlrev_b32_e32 v160, 4, v1
	v_lshl_add_u64 v[86:87], v[84:85], 2, s[0:1]
	v_add_u32_e32 v1, 0xe3, v0
	s_movk_i32 s0, 0x1c7
	v_cmp_gt_u32_e64 s[0:1], s0, v1
	s_ashr_i32 s14, s10, 6
	v_lshl_add_u64 v[2:3], v[84:85], 1, s[46:47]
	v_writelane_b32 v242, s0, 41
	v_and_b32_e32 v139, 15, v0
	v_bfe_u32 v4, v0, 4, 2
	v_writelane_b32 v242, s1, 42
	s_movk_i32 s0, 0x1c6
	v_cmp_lt_u32_e64 s[88:89], s0, v1
	s_mov_b64 s[0:1], 0x5500000
	v_lshl_add_u64 v[88:89], v[2:3], 0, s[0:1]
	s_and_b64 s[0:1], s[34:35], exec
	s_movk_i32 s0, 0xd0
	v_cmp_gt_u32_e32 vcc, s0, v5
	s_movk_i32 s0, 0xc7
	v_add_u32_e32 v0, 0xffffff1c, v0
	v_cndmask_b32_e64 v1, 2, 0, vcc
	v_cmp_lt_u32_e32 vcc, s0, v5
	s_movk_i32 s0, 0xbf
	s_cselect_b32 s77, 32, 0
	v_cndmask_b32_e32 v1, 1, v1, vcc
	v_cmp_lt_i32_e32 vcc, s0, v5
	v_cmp_gt_u32_e64 s[0:1], s15, v0
	s_cselect_b32 s91, 2, 0
	s_cmp_lt_i32 s14, 4
	v_writelane_b32 v242, s0, 43
	v_cndmask_b32_e32 v162, 0, v1, vcc
	v_lshlrev_b32_e32 v128, 4, v4
	v_writelane_b32 v242, s1, 44
	s_cselect_b64 s[0:1], -1, 0
	v_writelane_b32 v242, s0, 45
	s_ashr_i32 s17, s10, 7
	v_lshl_add_u32 v163, v5, 4, 0
	v_writelane_b32 v242, s1, 46
	s_lshl_b32 s0, s14, 4
	v_and_or_b32 v0, s0, 16, v139
	s_lshl_b32 s0, s17, 5
	v_readlane_b32 s29, v242, 18
	s_add_i32 s0, s0, s29
	v_mov_b32_e32 v1, s0
	s_movk_i32 s0, 0x50
	v_mul_u32_u24_e32 v5, 0xe50, v0
	v_mad_u32_u24 v6, v0, s0, v1
	v_lshl_add_u64 v[0:1], s[46:47], 0, v[128:129]
	s_mov_b64 s[0:1], 0x2000000
	v_lshl_add_u64 v[90:91], v[0:1], 0, s[0:1]
	s_mov_b64 s[0:1], 0x2010000
	v_lshl_add_u64 v[92:93], v[0:1], 0, s[0:1]
	s_mov_b64 s[0:1], 0x2020000
	v_lshl_add_u64 v[94:95], v[0:1], 0, s[0:1]
	s_mov_b64 s[0:1], 0x2050000
	v_lshl_add_u64 v[96:97], v[0:1], 0, s[0:1]
	v_and_b32_e32 v1, 64, v189
	v_xor_b32_e32 v0, 16, v189
	v_add_u32_e32 v1, 64, v1
	s_and_b32 s15, s10, 0xffffffc0
	v_cmp_lt_i32_e32 vcc, v0, v1
	s_add_u32 s42, s46, s16
	s_addc_u32 s43, s47, 0
	v_cndmask_b32_e32 v0, v189, v0, vcc
	v_lshlrev_b32_e32 v164, 2, v0
	v_xor_b32_e32 v0, 32, v189
	v_lshl_or_b32 v98, v4, 2, s15
	s_ashr_i32 s15, s14, 31
	v_cmp_lt_i32_e32 vcc, v0, v1
	s_lshl_b64 s[0:1], s[14:15], 2
	s_add_u32 s0, s46, s0
	v_cndmask_b32_e32 v0, v189, v0, vcc
	v_lshlrev_b32_e32 v2, 9, v139
	v_lshlrev_b32_e32 v165, 2, v0
	s_addc_u32 s1, s47, s1
	v_mad_u32_u24 v0, v139, s75, 0
	v_lshlrev_b32_e32 v8, 1, v98
	s_add_u32 s40, s0, 0x20c0000
	v_add_u32_e32 v166, v0, v128
	v_add_u32_e32 v1, 0xe500, v0
	v_add_u32_e32 v169, v0, v8
	v_lshl_or_b32 v0, s17, 13, v2
	s_addc_u32 s41, s1, 0
	v_add_u32_e32 v168, v1, v128
	v_add_u32_e32 v170, v1, v8
	s_add_i32 s0, 0, 0x800
	v_ashrrev_i32_e32 v1, 31, v0
	v_add3_u32 v171, v5, v128, s0
	v_lshlrev_b64 v[0:1], 1, v[0:1]
	s_lshr_b32 s0, s10, 6
	v_or_b32_e32 v0, v0, v128
	s_lshl_b32 s1, s0, 7
	v_lshl_add_u64 v[106:107], s[46:47], 0, v[0:1]
	v_mov_b32_e32 v0, s1
	v_lshlrev_b32_e32 v3, 3, v4
	v_mad_u32_u24 v0, v139, s75, v0
	v_add_u32_e32 v7, s29, v128
	v_add3_u32 v128, v0, v3, 0
	v_lshlrev_b32_e32 v0, 5, v139
	s_mul_i32 s1, s0, 0x2800
	v_lshl_or_b32 v172, s0, 11, v0
	v_mov_b32_e32 v0, s1
	v_mad_u32_u24 v173, v139, s58, v0
	v_lshlrev_b32_e32 v0, 6, v139
	v_cmp_eq_u32_e64 s[44:45], 0, v4
	v_mul_u32_u24_e32 v4, 0x50, v139
	v_or_b32_e32 v100, 16, v98
	v_or_b32_e32 v102, 32, v98
	v_or_b32_e32 v104, 48, v98
	v_lshl_or_b32 v174, s0, 12, v0
	v_readlane_b32 s0, v242, 39
	v_add_u32_e32 v161, -1, v160
	v_or_b32_e32 v167, 16, v139
	v_ashrrev_i32_e32 v99, 31, v98
	v_ashrrev_i32_e32 v101, 31, v100
	v_ashrrev_i32_e32 v103, 31, v102
	v_ashrrev_i32_e32 v105, 31, v104
	v_add_u32_e32 v175, v6, v3
	v_add_u32_e32 v176, v7, v4
	v_readlane_b32 s1, v242, 40
	s_branch .LBB0_607

; #define INP(p, i) ldp((p).tbl, i)
; __device__ void phase_prep(const Ctx& p, int l, LAS unsigned char* lds) {
;     ...
;             if (seq_start) {
;                 if (t0 >= T_P) { const float* sp = INP(p, 2) + ((size_t)l * 32 + (t0 - T_P) / 32) * 1824 + c0;
; #pragma unroll
;                     for (int j = 0; j < 8; ++j) prev[j] = sp[j]; }
.LBB0_613:
	v_mov_b32_e32 v39, 0
	v_mov_b32_e32 v38, 0
	v_mov_b32_e32 v37, 0
	v_mov_b32_e32 v36, 0
	v_mov_b32_e32 v43, 0
	v_mov_b32_e32 v42, 0
	v_mov_b32_e32 v41, 0
	v_mov_b32_e32 v40, 0
	s_and_saveexec_b64 s[60:61], s[0:1]
	s_cbranch_execz .LBB0_615
	v_mov_b64_e32 v[8:9], s[92:93]
	s_waitcnt vmcnt(0)
	s_add_i32 s10, s76, 0xffffc000
	s_lshr_b32 s10, s10, 5
	s_add_i32 s10, s10, s77
	s_mul_hi_u32 s15, s10, 0x1c80
	s_mulk_i32 s10, 0x1c80
	s_waitcnt lgkmcnt(0)
	s_load_dword s14, s[92:93], 0x10
	s_load_dword s16, s[92:93], 0x14
	s_waitcnt lgkmcnt(0)
	s_add_u32 s14, s14, s10
	s_addc_u32 s15, s16, s15
	v_lshl_add_u64 v[8:9], v[84:85], 2, s[14:15]
	global_load_dwordx4 v[40:43], v[8:9], off
	global_load_dwordx4 v[36:39], v[8:9], off offset:16

; __device__ __forceinline__ int tidx() { int t = threadIdx.x; asm volatile("" : "+v"(t)); return t; }
; #define INP(p, i) ldp((p).tbl, i)
; __device__ void conv_T(const float* __restrict__ src, int ld, int s0, int cnt, int K, const float* __restrict__ scale, bf16_t* __restrict__ dst, int d0, LAS unsigned char* lds, int vb, int nvb) {
;     LAS float* ts = (LAS float*)lds;
;     const int tid = tidx(); const int nkt = K / 256, ntile = (cnt / 32) * nkt;
;     if (vb < 0) return;
;     for (int tile = vb; tile < ntile; tile += nvb) {
;         const int n0 = (tile / nkt) * 32, k0 = (tile % nkt) * 256;
; __device__ void phase_convert_early(const Ctx& p, int l, LAS unsigned char* lds, int vb, int nvb) {
;     unsigned char* ws = uptr(p.ws);
;     const float* win = INP(p, 6) + (size_t)l * 1024 * 5920; const float* nm = INP(p, 5) + l * 1024;
;     conv_T(win, 5920, 0, 1824, 1024, nm, (bf16_t*)(ws + OFF_WRW), 0, lds, vb, nvb);
.LBB0_1212:
	v_readlane_b32 s30, v242, 31
	v_readlane_b32 s34, v242, 33
	s_and_b64 vcc, exec, s[36:37]
	v_readlane_b32 s31, v242, 32
	v_readlane_b32 s35, v242, 34
	s_cbranch_vccz .LBB0_1269
	v_readlane_b32 s2, v242, 35
	v_readlane_b32 s3, v242, 36
	s_mov_b64 s[0:1], -1
	s_and_b64 vcc, exec, s[2:3]
	s_cbranch_vccz .LBB0_1261
	s_mov_b32 s10, s90
	s_mov_b32 s1, s87
	s_mov_b32 s0, s86
	v_mov_b64_e32 v[0:1], s[92:93]
	s_waitcnt vmcnt(0) lgkmcnt(0)
	s_waitcnt vmcnt(0)
	v_mov_b32_e32 v0, v184
	s_cmpk_gt_u32 s10, 0xe3
	s_load_dword s5, s[92:93], 0x34
	s_load_dword s4, s[92:93], 0x30
	s_waitcnt lgkmcnt(0)
	s_waitcnt lgkmcnt(0)
	s_load_dword s3, s[92:93], 0x2c
	s_load_dword s2, s[92:93], 0x28
	s_waitcnt lgkmcnt(0)
	s_cbranch_scc1 .LBB0_1225
	v_ashrrev_i32_e32 v20, 3, v0
	v_and_b32_e32 v1, 7, v0
	v_ashrrev_i32_e32 v22, 4, v0
	v_lshlrev_b32_e32 v0, 2, v0
	v_lshlrev_b32_e32 v128, 4, v1
	v_mul_u32_u24_e32 v1, 0x1010, v1
	v_lshlrev_b32_e32 v2, 2, v20
	s_movk_i32 s6, 0x404
	v_and_b32_e32 v0, 60, v0
	s_cmp_lg_u64 s[2:3], 0
	v_add3_u32 v21, 0, v1, v2
	v_mul_lo_u32 v1, v22, s6
	v_lshlrev_b32_e32 v2, 2, v0
	v_lshl_add_u64 v[16:17], s[4:5], 0, v[128:129]
	s_cselect_b64 s[4:5], -1, 0
	v_add3_u32 v23, 0, v1, v2
	s_lshl_b32 s12, s10, 8
	v_lshlrev_b32_e32 v128, 1, v0
	s_mov_b32 s13, s10
	s_branch .LBB0_1217

; __device__ __forceinline__ int tidx() { int t = threadIdx.x; asm volatile("" : "+v"(t)); return t; }
; #define INP(p, i) ldp((p).tbl, i)
; __device__ __forceinline__ unsigned short f2bf(float f) { unsigned u = __float_as_uint(f); u += 0x7FFFu + ((u >> 16) & 1u); return (unsigned short)(u >> 16); }
; __device__ void conv_small(const float* __restrict__ src, int ld, int cnt, int K, bf16_t* __restrict__ dst, int vb, int nvb) {
;     if (vb < 0) return;
;     for (int i = vb * 512 + tidx(); i < cnt * K; i += nvb * 512) { const int c = i / K, j = i % K; dst[i] = f2bf(src[(size_t)j * ld + c]); }
; __device__ void phase_convert_early(const Ctx& p, int l, LAS unsigned char* lds, int vb, int nvb) {
;     ...
;     conv_small(INP(p, 9) + (size_t)l * 64 * 512, 512, 512, 64, (bf16_t*)(ws + OFF_SM + SM_W2T), vb, nvb);
.LBB0_1230:
	v_mov_b64_e32 v[0:1], s[92:93]
	s_waitcnt vmcnt(0)
	s_cmp_gt_i32 s10, -1
	s_cselect_b64 s[2:3], -1, 0
	s_cmp_lt_i32 s10, 0
	s_waitcnt lgkmcnt(0)
	s_load_dword s5, s[92:93], 0x4c
	s_load_dword s4, s[92:93], 0x48
	s_waitcnt lgkmcnt(0)
	s_cbranch_scc1 .LBB0_1240
	v_mov_b32_e32 v0, v184
	s_mov_b32 s6, 0x8000
	v_lshl_add_u32 v0, s10, 9, v0
	v_cmp_gt_i32_e32 vcc, s6, v0
	s_and_saveexec_b64 s[6:7], vcc
	v_readlane_b32 s16, v242, 9
	v_readlane_b32 s17, v242, 10
	s_cbranch_execz .LBB0_1239
	v_add_u32_e32 v1, s74, v0
	s_mov_b32 s14, 0x8000
	v_max_i32_e32 v2, 0x8000, v1
	v_cmp_gt_i32_e32 vcc, s14, v1
	s_add_u32 s12, s0, 0x2000000
	s_addc_u32 s13, s1, 0
	v_cndmask_b32_e64 v3, 1, 2, vcc
	v_subb_co_u32_e32 v1, vcc, v2, v1, vcc
	v_mul_hi_u32 v2, v1, v186
	v_mul_lo_u32 v4, v2, s74
	v_sub_u32_e32 v1, v1, v4
	v_add_u32_e32 v4, 1, v2
	v_cmp_le_u32_e32 vcc, s74, v1
	s_mov_b64 s[22:23], -1
	s_nop 0
	v_cndmask_b32_e32 v2, v2, v4, vcc
	v_subrev_u32_e32 v4, s74, v1
	v_cndmask_b32_e32 v1, v1, v4, vcc
	v_add_u32_e32 v4, 1, v2
	v_cmp_le_u32_e32 vcc, s74, v1
	s_nop 1
	v_cndmask_b32_e32 v1, v2, v4, vcc
	v_add_u32_e32 v3, v3, v1
	v_cmp_lt_u32_e32 vcc, 1, v3
	s_and_saveexec_b64 s[20:21], vcc
	s_cbranch_execz .LBB0_1236
	v_readlane_b32 s14, v242, 5
	v_and_b32_e32 v4, -2, v3
	v_readlane_b32 s15, v242, 6
	v_add_u32_e32 v2, s14, v0
	s_mov_b64 s[22:23], 0
	v_add_u32_e32 v1, s15, v0
	v_mov_b32_e32 v5, v4

; __device__ __forceinline__ int tidx() { int t = threadIdx.x; asm volatile("" : "+v"(t)); return t; }
; #define INP(p, i) ldp((p).tbl, i)
; __device__ __forceinline__ unsigned short f2bf(float f) { unsigned u = __float_as_uint(f); u += 0x7FFFu + ((u >> 16) & 1u); return (unsigned short)(u >> 16); }
; __device__ void conv_small(const float* __restrict__ src, int ld, int cnt, int K, bf16_t* __restrict__ dst, int vb, int nvb) {
;     if (vb < 0) return;
;     for (int i = vb * 512 + tidx(); i < cnt * K; i += nvb * 512) { const int c = i / K, j = i % K; dst[i] = f2bf(src[(size_t)j * ld + c]); }
; __device__ void phase_convert_early(const Ctx& p, int l, LAS unsigned char* lds, int vb, int nvb) {
;     ...
;     conv_small(INP(p, 11) + (size_t)l * 64 * 512, 512, 512, 64, (bf16_t*)(ws + OFF_SM + SM_A2T), vb, nvb);
.LBB0_1240:
	v_mov_b64_e32 v[0:1], s[92:93]
	s_waitcnt vmcnt(0)
	v_cndmask_b32_e64 v2, 0, 1, s[2:3]
	v_cmp_ne_u32_e64 s[38:39], 1, v2
	s_andn2_b64 vcc, exec, s[2:3]
	s_waitcnt lgkmcnt(0)
	s_load_dword s3, s[92:93], 0x5c
	s_load_dword s2, s[92:93], 0x58
	s_waitcnt lgkmcnt(0)
	s_cbranch_vccnz .LBB0_1250
	v_mov_b32_e32 v0, v184
	s_mov_b32 s4, 0x8000
	v_lshl_add_u32 v0, s10, 9, v0
	v_cmp_gt_i32_e32 vcc, s4, v0
	s_and_saveexec_b64 s[4:5], vcc
	s_cbranch_execz .LBB0_1249
	v_add_u32_e32 v1, s74, v0
	s_mov_b32 s12, 0x8000
	v_max_i32_e32 v2, 0x8000, v1
	v_cmp_gt_i32_e32 vcc, s12, v1
	s_add_u32 s6, s0, 0x2010000
	s_addc_u32 s7, s1, 0
	v_cndmask_b32_e64 v3, 1, 2, vcc
	v_subb_co_u32_e32 v1, vcc, v2, v1, vcc
	v_mul_hi_u32 v2, v1, v186
	v_mul_lo_u32 v4, v2, s74
	v_sub_u32_e32 v1, v1, v4
	v_add_u32_e32 v4, 1, v2
	v_cmp_le_u32_e32 vcc, s74, v1
	s_mov_b64 s[20:21], -1
	s_nop 0
	v_cndmask_b32_e32 v2, v2, v4, vcc
	v_subrev_u32_e32 v4, s74, v1
	v_cndmask_b32_e32 v1, v1, v4, vcc
	v_add_u32_e32 v4, 1, v2
	v_cmp_le_u32_e32 vcc, s74, v1
	s_nop 1
	v_cndmask_b32_e32 v1, v2, v4, vcc
	v_add_u32_e32 v3, v3, v1
	v_cmp_lt_u32_e32 vcc, 1, v3
	s_and_saveexec_b64 s[12:13], vcc
	s_cbranch_execz .LBB0_1246
	v_readlane_b32 s14, v242, 5
	v_and_b32_e32 v4, -2, v3
	v_readlane_b32 s15, v242, 6
	v_add_u32_e32 v2, s14, v0
	s_mov_b64 s[20:21], 0
	v_add_u32_e32 v1, s15, v0
	v_mov_b32_e32 v5, v4
	v_readlane_b32 s14, v242, 9
	v_readlane_b32 s15, v242, 10

; __device__ __forceinline__ int tidx() { int t = threadIdx.x; asm volatile("" : "+v"(t)); return t; }
; #define INP(p, i) ldp((p).tbl, i)
; __device__ __forceinline__ unsigned short f2bf(float f) { unsigned u = __float_as_uint(f); u += 0x7FFFu + ((u >> 16) & 1u); return (unsigned short)(u >> 16); }
; __device__ void conv_small(const float* __restrict__ src, int ld, int cnt, int K, bf16_t* __restrict__ dst, int vb, int nvb) {
;     if (vb < 0) return;
;     for (int i = vb * 512 + tidx(); i < cnt * K; i += nvb * 512) { const int c = i / K, j = i % K; dst[i] = f2bf(src[(size_t)j * ld + c]); }
; __device__ void phase_convert_early(const Ctx& p, int l, LAS unsigned char* lds, int vb, int nvb) {
;     ...
;     conv_small(INP(p, 12) + (size_t)l * 160 * 512, 512, 512, 160, (bf16_t*)(ws + OFF_SM + SM_G2T), vb, nvb);
.LBB0_1250:
	v_mov_b64_e32 v[0:1], s[92:93]
	s_waitcnt vmcnt(0)
	s_and_b64 vcc, exec, s[38:39]
	v_readlane_b32 s16, v242, 9
	v_readlane_b32 s17, v242, 10
	v_readlane_b32 s39, v242, 28
	s_mov_b32 s20, 0x13fff
	s_mov_b32 s38, 0x1ffff
	s_waitcnt lgkmcnt(0)
	s_load_dword s3, s[92:93], 0x64
	s_load_dword s2, s[92:93], 0x60
	s_waitcnt lgkmcnt(0)
	s_cbranch_vccnz .LBB0_1260
	v_mov_b32_e32 v0, v184
	s_mov_b32 s4, 0x14000
	v_lshl_add_u32 v0, s10, 9, v0
	v_cmp_gt_i32_e32 vcc, s4, v0
	s_and_saveexec_b64 s[4:5], vcc
	s_mov_b32 s10, 0x66666667
	s_cbranch_execz .LBB0_1259
	v_add_u32_e32 v1, s74, v0
	s_mov_b32 s6, 0x14000
	v_max_i32_e32 v2, 0x14000, v1
	v_cmp_gt_i32_e32 vcc, s6, v1
	s_add_u32 s0, s0, 0x2020000
	s_addc_u32 s1, s1, 0
	v_cndmask_b32_e64 v3, 1, 2, vcc
	v_subb_co_u32_e32 v1, vcc, v2, v1, vcc
	v_mul_hi_u32 v2, v1, v186
	v_mul_lo_u32 v4, v2, s74
	v_sub_u32_e32 v1, v1, v4
	v_add_u32_e32 v4, 1, v2
	v_cmp_le_u32_e32 vcc, s74, v1
	s_mov_b64 s[12:13], -1
	s_nop 0
	v_cndmask_b32_e32 v2, v2, v4, vcc
	v_subrev_u32_e32 v4, s74, v1
	v_cndmask_b32_e32 v1, v1, v4, vcc
	v_add_u32_e32 v4, 1, v2
	v_cmp_le_u32_e32 vcc, s74, v1
	s_nop 1
	v_cndmask_b32_e32 v1, v2, v4, vcc
	v_add_u32_e32 v3, v3, v1
	v_cmp_lt_u32_e32 vcc, 1, v3
	s_and_saveexec_b64 s[6:7], vcc
	s_cbranch_execz .LBB0_1256
	v_readlane_b32 s12, v242, 5
	v_and_b32_e32 v4, -2, v3
	v_readlane_b32 s13, v242, 6
	v_add_u32_e32 v2, s12, v0
	v_mov_b32_e32 v5, v4
	v_add_u32_e32 v1, s13, v0
	s_mov_b64 s[12:13], 0

; __device__ __forceinline__ int tidx() { int t = threadIdx.x; asm volatile("" : "+v"(t)); return t; }
; #define INP(p, i) ldp((p).tbl, i)
; __device__ void conv_T(const float* __restrict__ src, int ld, int s0, int cnt, int K, const float* __restrict__ scale, bf16_t* __restrict__ dst, int d0, LAS unsigned char* lds, int vb, int nvb) {
;     LAS float* ts = (LAS float*)lds;
;     const int tid = tidx(); const int nkt = K / 256, ntile = (cnt / 32) * nkt;
;     if (vb < 0) return;
;     for (int tile = vb; tile < ntile; tile += nvb) {
;         const int n0 = (tile / nkt) * 32, k0 = (tile % nkt) * 256;
; __device__ void phase_convert_hg(const Ctx& p, int l, LAS unsigned char* lds, int vb, int nvb) {
;     unsigned char* ws = uptr(p.ws);
;     conv_T(INP(p, 6) + (size_t)l * 1024 * 5920, 5920, 1824, 2048, 1024, INP(p, 5) + l * 1024, (bf16_t*)(ws + OFF_WHG), 0, lds, vb, nvb);
.LBB0_1314:
	s_mov_b32 s2, s90
	s_mov_b32 s4, s86
	s_mov_b32 s5, s87
	v_mov_b64_e32 v[0:1], s[92:93]
	s_waitcnt vmcnt(0)
	s_max_i32 s2, s2, 31
	s_waitcnt vmcnt(0)
	s_sub_i32 s10, s2, 32
	v_readlane_b32 s46, v242, 24
	v_readlane_b32 s88, v242, 39
	s_cmpk_gt_u32 s10, 0xff
	v_readlane_b32 s47, v242, 25
	v_readlane_b32 s29, v242, 27
	s_movk_i32 s77, 0xa0
	s_movk_i32 s58, 0xff60
	v_readlane_b32 s89, v242, 40
	s_mov_b32 s65, s79
	s_waitcnt lgkmcnt(0)
	s_load_dword s12, s[92:93], 0x34
	s_load_dword s13, s[92:93], 0x30
	s_waitcnt lgkmcnt(0)
	s_load_dword s7, s[92:93], 0x2c
	s_load_dword s6, s[92:93], 0x28
	s_waitcnt lgkmcnt(0)
	v_mov_b32_e32 v0, v184
	s_cbranch_scc1 .LBB0_1331
	s_and_b64 s[2:3], s[34:35], exec
	s_cselect_b32 s2, 0x1000, 0
	s_add_u32 s2, s6, s2
	s_addc_u32 s3, s7, 0
	s_add_u32 s4, s4, 0x400000
	s_addc_u32 s5, s5, 0
	s_and_b64 s[14:15], s[34:35], exec
	s_cselect_b32 s14, 0x1720000, 0
	s_add_u32 s14, s13, s14
	v_and_b32_e32 v1, 7, v0
	s_addc_u32 s15, s12, 0
	v_lshlrev_b32_e32 v128, 4, v1
	v_ashrrev_i32_e32 v20, 3, v0
	v_lshl_add_u64 v[2:3], s[14:15], 0, v[128:129]
	s_mov_b64 s[12:13], 0x1c80
	v_ashrrev_i32_e32 v22, 4, v0
	v_lshlrev_b32_e32 v0, 2, v0
	v_lshl_add_u64 v[16:17], v[2:3], 0, s[12:13]
	v_mul_u32_u24_e32 v1, 0x1010, v1
	v_lshlrev_b32_e32 v2, 2, v20
	s_movk_i32 s12, 0x404
	v_and_b32_e32 v0, 60, v0
	s_cmp_lg_u64 s[6:7], 0
	v_add3_u32 v21, 0, v1, v2
	v_mul_lo_u32 v1, v22, s12
	v_lshlrev_b32_e32 v2, 2, v0
	s_cselect_b64 s[6:7], -1, 0
	v_add3_u32 v23, 0, v1, v2
	s_lshl_b32 s14, s10, 8
	s_lshl_b32 s15, s51, 8
	v_lshlrev_b32_e32 v128, 1, v0
	s_branch .LBB0_1317

; __device__ __forceinline__ int tidx() { int t = threadIdx.x; asm volatile("" : "+v"(t)); return t; }
; __device__ __forceinline__ int bidx() { int b = blockIdx.x; asm volatile("" : "+s"(b)); return b; }
; #define INP(p, i) ldp((p).tbl, i)
; __device__ void phase_final(const Ctx& p) {
;     const int tid = tidx(); const int wave = __builtin_amdgcn_readfirstlane(tid >> 6), lane = tid & 63;
;     const float* nf = INP(p, 29); const float* PART = (const float*)(uptr(p.ws) + OFF_PART);
;     for (int row = bidx() * 8 + wave; row < T_ALL; row += gridDim.x * 8) {
;         float* xp = p.out + (size_t)row * 1024; float4 v[4]; float ss = 0.f;
; #pragma unroll
;         for (int i = 0; i < 4; ++i) { v[i] = *(const float4*)(xp + i * 256 + lane * 4);
;             if (row >= T_P) { const float* pr = PART + (size_t)(row - T_P) * 1024 + i * 256 + lane * 4;
; #pragma unroll
;                 for (int sl = 0; sl < 8; ++sl) { const float4 q = *(const float4*)(pr + (size_t)sl * 1024 * 1024); v[i].x += q.x; v[i].y += q.y; v[i].z += q.z; v[i].w += q.w; } }
;             ss += v[i].x * v[i].x + v[i].y * v[i].y + v[i].z * v[i].z + v[i].w * v[i].w; }
;         const float s = rsqrtf(wsum(ss) * (1.0f / 1024.0f) + 1e-6f);
.LBB0_1412:
	v_mov_b64_e32 v[0:1], s[92:93]
	s_waitcnt vmcnt(0)
	s_mov_b32 s3, s87
	v_readfirstlane_b32 s0, v184
	s_ashr_i32 s0, s0, 6
	s_lshl_b32 s1, s90, 3
	s_add_i32 s2, s1, s0
	s_cmpk_gt_i32 s2, 0x43ff
	s_waitcnt lgkmcnt(0)
	s_load_dword s1, s[92:93], 0xec
	s_load_dword s0, s[92:93], 0xe8
	s_waitcnt lgkmcnt(0)
	s_cbranch_scc1 .LBB0_1423
	v_lshlrev_b32_e32 v0, 4, v184
	s_mov_b32 s87, s3
	v_and_b32_e32 v0, 0x3f0, v0
	v_mov_b32_e32 v1, 0
	v_lshl_add_u64 v[2:3], s[86:87], 0, v[0:1]
	s_mov_b64 s[4:5], 0xdd00000
	v_lshl_add_u64 v[16:17], v[2:3], 0, s[4:5]
	v_and_b32_e32 v2, 64, v189
	v_add_u32_e32 v2, 64, v2
	v_xor_b32_e32 v3, 32, v189
	v_cmp_lt_i32_e32 vcc, v3, v2
	s_mov_b32 s5, 0
	v_lshl_add_u64 v[18:19], s[0:1], 0, v[0:1]
	v_cndmask_b32_e32 v3, v189, v3, vcc
	v_lshlrev_b32_e32 v26, 2, v3
	v_xor_b32_e32 v3, 16, v189
	v_cmp_lt_i32_e32 vcc, v3, v2
	v_lshl_add_u64 v[20:21], s[84:85], 0, v[0:1]
	s_mov_b32 s8, 0x800000
	v_cndmask_b32_e32 v3, v189, v3, vcc
	v_lshlrev_b32_e32 v27, 2, v3
	v_xor_b32_e32 v3, 8, v189
	v_cmp_lt_i32_e32 vcc, v3, v2
	v_mov_b32_e32 v32, 0x358637bd
	s_nop 0
	v_cndmask_b32_e32 v3, v189, v3, vcc
	v_lshlrev_b32_e32 v28, 2, v3
	v_xor_b32_e32 v3, 4, v189
	v_cmp_lt_i32_e32 vcc, v3, v2
	s_nop 1
	v_cndmask_b32_e32 v3, v189, v3, vcc
	v_lshlrev_b32_e32 v29, 2, v3
	v_xor_b32_e32 v3, 2, v189
	v_cmp_lt_i32_e32 vcc, v3, v2
	s_nop 1
	v_cndmask_b32_e32 v3, v189, v3, vcc
	v_lshlrev_b32_e32 v30, 2, v3
	v_xor_b32_e32 v3, 1, v189
	v_cmp_lt_i32_e32 vcc, v3, v2
	s_nop 1
	v_cndmask_b32_e32 v2, v189, v3, vcc
	v_lshlrev_b32_e32 v31, 2, v2
	s_branch .LBB0_1415
